# v27 + SCAN_B hand-written fast path (all 15 steps prefetched) + first K iteration peeled in 9 GEMM loops (first MFMA SrcC=0, acc zeroing removed)
# speedup vs baseline: 1.0298x; 1.0025x over previous
.LBB0_383:
	s_add_u32 s26, s0, s22
	s_addc_u32 s27, s1, s23
	s_and_b64 s[44:45], s[36:37], exec
	s_cselect_b32 s15, s27, s43
	s_cselect_b32 s39, s26, s42
	s_add_u32 s66, s42, 0x100
	s_addc_u32 s67, s43, 0
	s_mov_b32 s68, -2
	s_mov_b64 s[42:43], 0
	ds_read_b128 v[152:155], v146
	ds_read_b128 v[156:159], v146 offset:1024
	ds_read_b128 v[160:163], v146 offset:2048
	ds_read_b128 v[164:167], v146 offset:3072
	ds_read_b128 v[168:171], v147
	ds_read_b128 v[172:175], v147 offset:1024
	ds_read_b128 v[176:179], v147 offset:2048
	ds_read_b128 v[180:183], v147 offset:3072
	s_add_u32 s44, s42, 0x100
	s_addc_u32 s45, s43, 0
	s_add_u32 s46, s66, s42
	s_addc_u32 s47, s67, s43
	s_cmp_eq_u32 s68, 4
	s_cselect_b32 s48, 0, s44
	s_cselect_b32 s49, 0, s45
	s_cselect_b32 s46, s39, s46
	s_cselect_b32 s47, s15, s47
	s_add_u32 s48, s6, s48
	s_addc_u32 s49, s7, s49
	s_mov_b32 m0, s29
	v_lshl_add_u64 v[218:219], v[138:139], 0, s[42:43]
	ds_read_b128 v[184:187], v148
	ds_read_b128 v[188:191], v148 offset:1024
	ds_read_b128 v[192:195], v148 offset:2048
	ds_read_b128 v[196:199], v148 offset:3072
	ds_read_b128 v[200:203], v148 offset:4096
	ds_read_b128 v[206:209], v148 offset:5120
	ds_read_b128 v[210:213], v148 offset:6144
	ds_read_b128 v[214:217], v148 offset:7168
	global_load_lds_dwordx4 v[218:219], off
	v_lshl_add_u64 v[218:219], v[140:141], 0, s[42:43]
	s_mov_b32 m0, s30
	s_nop 0
	global_load_lds_dwordx4 v[218:219], off
	s_waitcnt vmcnt(8)
	s_waitcnt lgkmcnt(0)
	s_barrier
	s_setprio 1
	s_waitcnt lgkmcnt(0)
	v_mfma_f32_16x16x32_bf16 v[126:129], v[152:155], v[184:187], 0
	v_mfma_f32_16x16x32_bf16 v[122:125], v[160:163], v[184:187], 0
	v_mfma_f32_16x16x32_bf16 v[118:121], v[152:155], v[192:195], 0
	v_mfma_f32_16x16x32_bf16 v[114:117], v[160:163], v[192:195], 0
	v_mfma_f32_16x16x32_bf16 v[102:105], v[152:155], v[200:203], 0
	v_mfma_f32_16x16x32_bf16 v[98:101], v[160:163], v[200:203], 0
	v_mfma_f32_16x16x32_bf16 v[86:89], v[152:155], v[210:213], 0
	v_mfma_f32_16x16x32_bf16 v[82:85], v[160:163], v[210:213], 0
	v_mfma_f32_16x16x32_bf16 v[126:129], v[156:159], v[188:191], v[126:129]
	v_mfma_f32_16x16x32_bf16 v[122:125], v[164:167], v[188:191], v[122:125]
	v_mfma_f32_16x16x32_bf16 v[118:121], v[156:159], v[196:199], v[118:121]
	v_mfma_f32_16x16x32_bf16 v[114:117], v[164:167], v[196:199], v[114:117]
	v_mfma_f32_16x16x32_bf16 v[102:105], v[156:159], v[206:209], v[102:105]
	v_mfma_f32_16x16x32_bf16 v[98:101], v[164:167], v[206:209], v[98:101]
	v_mfma_f32_16x16x32_bf16 v[86:89], v[156:159], v[214:217], v[86:89]
	v_mfma_f32_16x16x32_bf16 v[82:85], v[164:167], v[214:217], v[82:85]
	s_setprio 0
	s_setprio 1
	v_mfma_f32_16x16x32_bf16 v[110:113], v[168:171], v[184:187], 0
	v_mfma_f32_16x16x32_bf16 v[106:109], v[176:179], v[184:187], 0
	v_mfma_f32_16x16x32_bf16 v[94:97], v[168:171], v[192:195], 0
	v_mfma_f32_16x16x32_bf16 v[90:93], v[176:179], v[192:195], 0
	v_mfma_f32_16x16x32_bf16 v[78:81], v[168:171], v[200:203], 0
	v_mfma_f32_16x16x32_bf16 v[74:77], v[176:179], v[200:203], 0
	v_mfma_f32_16x16x32_bf16 v[70:73], v[168:171], v[210:213], 0
	v_mfma_f32_16x16x32_bf16 v[66:69], v[176:179], v[210:213], 0
	v_mfma_f32_16x16x32_bf16 v[110:113], v[172:175], v[188:191], v[110:113]
	v_mfma_f32_16x16x32_bf16 v[106:109], v[180:183], v[188:191], v[106:109]
	v_mfma_f32_16x16x32_bf16 v[94:97], v[172:175], v[196:199], v[94:97]
	v_mfma_f32_16x16x32_bf16 v[90:93], v[180:183], v[196:199], v[90:93]
	v_mfma_f32_16x16x32_bf16 v[78:81], v[172:175], v[206:209], v[78:81]
	v_mfma_f32_16x16x32_bf16 v[74:77], v[180:183], v[206:209], v[74:77]
	v_mfma_f32_16x16x32_bf16 v[70:73], v[172:175], v[214:217], v[70:73]
	v_mfma_f32_16x16x32_bf16 v[66:69], v[180:183], v[214:217], v[66:69]
	s_setprio 0
	s_barrier
	s_mov_b32 m0, s31
	v_lshl_add_u64 v[218:219], s[46:47], 0, v[134:135]
	s_add_u32 s42, s46, 0x20000
	ds_read_b128 v[184:187], v148 offset:16384
	ds_read_b128 v[188:191], v148 offset:17408
	ds_read_b128 v[192:195], v148 offset:18432
	ds_read_b128 v[196:199], v148 offset:19456
	ds_read_b128 v[200:203], v148 offset:20480
	ds_read_b128 v[206:209], v148 offset:21504
	ds_read_b128 v[210:213], v148 offset:22528
	ds_read_b128 v[214:217], v148 offset:23552
	global_load_lds_dwordx4 v[218:219], off
	v_lshl_add_u64 v[220:221], s[46:47], 0, v[130:131]
	s_mov_b32 m0, s33
	s_addc_u32 s43, s47, 0
	global_load_lds_dwordx4 v[220:221], off
	v_lshl_add_u64 v[222:223], s[42:43], 0, v[134:135]
	s_mov_b32 m0, s34
	v_lshl_add_u64 v[224:225], s[48:49], 0, v[132:133]
	global_load_lds_dwordx4 v[222:223], off
	v_lshl_add_u64 v[222:223], s[42:43], 0, v[130:131]
	s_mov_b32 m0, s35
	s_nop 0
	global_load_lds_dwordx4 v[222:223], off
	v_lshl_add_u64 v[222:223], s[48:49], 0, v[136:137]
	s_mov_b32 m0, s2
	s_nop 0
	global_load_lds_dwordx4 v[222:223], off
	s_mov_b32 m0, s3
	s_nop 0
	global_load_lds_dwordx4 v[224:225], off
	s_waitcnt vmcnt(8)
	s_waitcnt lgkmcnt(0)
	s_barrier
	s_setprio 1
	s_waitcnt lgkmcnt(0)
	v_mfma_f32_16x16x32_bf16 v[62:65], v[152:155], v[184:187], 0
	v_mfma_f32_16x16x32_bf16 v[58:61], v[160:163], v[184:187], 0
	v_mfma_f32_16x16x32_bf16 v[54:57], v[152:155], v[192:195], 0
	v_mfma_f32_16x16x32_bf16 v[50:53], v[160:163], v[192:195], 0
	v_mfma_f32_16x16x32_bf16 v[38:41], v[152:155], v[200:203], 0
	v_mfma_f32_16x16x32_bf16 v[34:37], v[160:163], v[200:203], 0
	v_mfma_f32_16x16x32_bf16 v[22:25], v[152:155], v[210:213], 0
	v_mfma_f32_16x16x32_bf16 v[18:21], v[160:163], v[210:213], 0
	v_mfma_f32_16x16x32_bf16 v[62:65], v[156:159], v[188:191], v[62:65]
	v_mfma_f32_16x16x32_bf16 v[58:61], v[164:167], v[188:191], v[58:61]
	v_mfma_f32_16x16x32_bf16 v[54:57], v[156:159], v[196:199], v[54:57]
	v_mfma_f32_16x16x32_bf16 v[50:53], v[164:167], v[196:199], v[50:53]
	v_mfma_f32_16x16x32_bf16 v[38:41], v[156:159], v[206:209], v[38:41]
	v_mfma_f32_16x16x32_bf16 v[34:37], v[164:167], v[206:209], v[34:37]
	v_mfma_f32_16x16x32_bf16 v[22:25], v[156:159], v[214:217], v[22:25]
	v_mfma_f32_16x16x32_bf16 v[18:21], v[164:167], v[214:217], v[18:21]
	s_setprio 0
	s_setprio 1
	v_mfma_f32_16x16x32_bf16 v[46:49], v[168:171], v[184:187], 0
	v_mfma_f32_16x16x32_bf16 v[42:45], v[176:179], v[184:187], 0
	v_mfma_f32_16x16x32_bf16 v[30:33], v[168:171], v[192:195], 0
	v_mfma_f32_16x16x32_bf16 v[26:29], v[176:179], v[192:195], 0
	v_mfma_f32_16x16x32_bf16 v[14:17], v[168:171], v[200:203], 0
	v_mfma_f32_16x16x32_bf16 v[10:13], v[176:179], v[200:203], 0
	v_mfma_f32_16x16x32_bf16 v[6:9], v[168:171], v[210:213], 0
	v_mfma_f32_16x16x32_bf16 v[2:5], v[176:179], v[210:213], 0
	v_mfma_f32_16x16x32_bf16 v[46:49], v[172:175], v[188:191], v[46:49]
	v_mfma_f32_16x16x32_bf16 v[42:45], v[180:183], v[188:191], v[42:45]
	v_mfma_f32_16x16x32_bf16 v[30:33], v[172:175], v[196:199], v[30:33]
	v_mfma_f32_16x16x32_bf16 v[26:29], v[180:183], v[196:199], v[26:29]
	v_mfma_f32_16x16x32_bf16 v[14:17], v[172:175], v[206:209], v[14:17]
	v_mfma_f32_16x16x32_bf16 v[10:13], v[180:183], v[206:209], v[10:13]
	v_mfma_f32_16x16x32_bf16 v[6:9], v[172:175], v[214:217], v[6:9]
	v_mfma_f32_16x16x32_bf16 v[2:5], v[180:183], v[214:217], v[2:5]
	s_setprio 0
	s_barrier
	ds_read_b128 v[152:155], v149
	ds_read_b128 v[156:159], v149 offset:1024
	ds_read_b128 v[160:163], v149 offset:2048
	ds_read_b128 v[164:167], v149 offset:3072
	ds_read_b128 v[168:171], v150
	ds_read_b128 v[172:175], v150 offset:1024
	ds_read_b128 v[176:179], v150 offset:2048
	ds_read_b128 v[180:183], v150 offset:3072
	s_add_u32 s42, s48, 0x20000
	s_addc_u32 s43, s49, 0
	s_mov_b32 m0, s16
	v_lshl_add_u64 v[226:227], s[42:43], 0, v[136:137]
	ds_read_b128 v[184:187], v148 offset:32768
	ds_read_b128 v[188:191], v148 offset:33792
	ds_read_b128 v[192:195], v148 offset:34816
	ds_read_b128 v[196:199], v148 offset:35840
	ds_read_b128 v[200:203], v148 offset:36864
	ds_read_b128 v[206:209], v148 offset:37888
	ds_read_b128 v[210:213], v148 offset:38912
	ds_read_b128 v[214:217], v148 offset:39936
	global_load_lds_dwordx4 v[226:227], off
	v_lshl_add_u64 v[226:227], s[42:43], 0, v[132:133]
	s_mov_b32 m0, s17
	s_nop 0
	global_load_lds_dwordx4 v[226:227], off
	s_waitcnt vmcnt(8)
	s_waitcnt lgkmcnt(0)
	s_barrier
	s_setprio 1
	s_waitcnt lgkmcnt(0)
	v_mfma_f32_16x16x32_bf16 v[126:129], v[152:155], v[184:187], v[126:129]
	v_mfma_f32_16x16x32_bf16 v[122:125], v[160:163], v[184:187], v[122:125]
	v_mfma_f32_16x16x32_bf16 v[118:121], v[152:155], v[192:195], v[118:121]
	v_mfma_f32_16x16x32_bf16 v[114:117], v[160:163], v[192:195], v[114:117]
	v_mfma_f32_16x16x32_bf16 v[102:105], v[152:155], v[200:203], v[102:105]
	v_mfma_f32_16x16x32_bf16 v[98:101], v[160:163], v[200:203], v[98:101]
	v_mfma_f32_16x16x32_bf16 v[86:89], v[152:155], v[210:213], v[86:89]
	v_mfma_f32_16x16x32_bf16 v[82:85], v[160:163], v[210:213], v[82:85]
	v_mfma_f32_16x16x32_bf16 v[126:129], v[156:159], v[188:191], v[126:129]
	v_mfma_f32_16x16x32_bf16 v[122:125], v[164:167], v[188:191], v[122:125]
	v_mfma_f32_16x16x32_bf16 v[118:121], v[156:159], v[196:199], v[118:121]
	v_mfma_f32_16x16x32_bf16 v[114:117], v[164:167], v[196:199], v[114:117]
	v_mfma_f32_16x16x32_bf16 v[102:105], v[156:159], v[206:209], v[102:105]
	v_mfma_f32_16x16x32_bf16 v[98:101], v[164:167], v[206:209], v[98:101]
	v_mfma_f32_16x16x32_bf16 v[86:89], v[156:159], v[214:217], v[86:89]
	v_mfma_f32_16x16x32_bf16 v[82:85], v[164:167], v[214:217], v[82:85]
	s_setprio 0
	s_setprio 1
	v_mfma_f32_16x16x32_bf16 v[110:113], v[168:171], v[184:187], v[110:113]
	v_mfma_f32_16x16x32_bf16 v[106:109], v[176:179], v[184:187], v[106:109]
	v_mfma_f32_16x16x32_bf16 v[94:97], v[168:171], v[192:195], v[94:97]
	v_mfma_f32_16x16x32_bf16 v[90:93], v[176:179], v[192:195], v[90:93]
	v_mfma_f32_16x16x32_bf16 v[78:81], v[168:171], v[200:203], v[78:81]
	v_mfma_f32_16x16x32_bf16 v[74:77], v[176:179], v[200:203], v[74:77]
	v_mfma_f32_16x16x32_bf16 v[70:73], v[168:171], v[210:213], v[70:73]
	v_mfma_f32_16x16x32_bf16 v[66:69], v[176:179], v[210:213], v[66:69]
	v_mfma_f32_16x16x32_bf16 v[110:113], v[172:175], v[188:191], v[110:113]
	v_mfma_f32_16x16x32_bf16 v[106:109], v[180:183], v[188:191], v[106:109]
	v_mfma_f32_16x16x32_bf16 v[94:97], v[172:175], v[196:199], v[94:97]
	v_mfma_f32_16x16x32_bf16 v[90:93], v[180:183], v[196:199], v[90:93]
	v_mfma_f32_16x16x32_bf16 v[78:81], v[172:175], v[206:209], v[78:81]
	v_mfma_f32_16x16x32_bf16 v[74:77], v[180:183], v[206:209], v[74:77]
	v_mfma_f32_16x16x32_bf16 v[70:73], v[172:175], v[214:217], v[70:73]
	v_mfma_f32_16x16x32_bf16 v[66:69], v[180:183], v[214:217], v[66:69]
	s_setprio 0
	s_barrier
	s_mov_b32 m0, s62
	v_lshl_add_u64 v[218:219], v[218:219], 0, s[10:11]
	s_add_u32 s42, s46, 0x20080
	ds_read_b128 v[184:187], v148 offset:49152
	ds_read_b128 v[188:191], v148 offset:50176
	ds_read_b128 v[192:195], v148 offset:51200
	ds_read_b128 v[196:199], v148 offset:52224
	ds_read_b128 v[200:203], v148 offset:53248
	ds_read_b128 v[206:209], v148 offset:54272
	ds_read_b128 v[210:213], v148 offset:55296
	ds_read_b128 v[214:217], v148 offset:56320
	global_load_lds_dwordx4 v[218:219], off
	v_lshl_add_u64 v[218:219], v[220:221], 0, s[10:11]
	s_mov_b32 m0, s63
	s_addc_u32 s43, s47, 0
	global_load_lds_dwordx4 v[218:219], off
	v_lshl_add_u64 v[218:219], s[42:43], 0, v[134:135]
	s_mov_b32 m0, s64
	s_nop 0
	global_load_lds_dwordx4 v[218:219], off
	v_lshl_add_u64 v[218:219], s[42:43], 0, v[130:131]
	s_mov_b32 m0, s65
	s_nop 0
	global_load_lds_dwordx4 v[218:219], off
	v_lshl_add_u64 v[218:219], v[222:223], 0, s[10:11]
	s_mov_b32 m0, s25
	s_nop 0
	global_load_lds_dwordx4 v[218:219], off
	v_lshl_add_u64 v[218:219], v[224:225], 0, s[10:11]
	s_mov_b32 m0, s28
	s_nop 0
	global_load_lds_dwordx4 v[218:219], off
	s_waitcnt vmcnt(8)
	s_waitcnt lgkmcnt(0)
	s_barrier
	s_setprio 1
	s_waitcnt lgkmcnt(0)
	v_mfma_f32_16x16x32_bf16 v[62:65], v[152:155], v[184:187], v[62:65]
	v_mfma_f32_16x16x32_bf16 v[58:61], v[160:163], v[184:187], v[58:61]
	v_mfma_f32_16x16x32_bf16 v[54:57], v[152:155], v[192:195], v[54:57]
	v_mfma_f32_16x16x32_bf16 v[50:53], v[160:163], v[192:195], v[50:53]
	v_mfma_f32_16x16x32_bf16 v[38:41], v[152:155], v[200:203], v[38:41]
	v_mfma_f32_16x16x32_bf16 v[34:37], v[160:163], v[200:203], v[34:37]
	v_mfma_f32_16x16x32_bf16 v[22:25], v[152:155], v[210:213], v[22:25]
	v_mfma_f32_16x16x32_bf16 v[18:21], v[160:163], v[210:213], v[18:21]
	v_mfma_f32_16x16x32_bf16 v[62:65], v[156:159], v[188:191], v[62:65]
	v_mfma_f32_16x16x32_bf16 v[58:61], v[164:167], v[188:191], v[58:61]
	v_mfma_f32_16x16x32_bf16 v[54:57], v[156:159], v[196:199], v[54:57]
	v_mfma_f32_16x16x32_bf16 v[50:53], v[164:167], v[196:199], v[50:53]
	v_mfma_f32_16x16x32_bf16 v[38:41], v[156:159], v[206:209], v[38:41]
	v_mfma_f32_16x16x32_bf16 v[34:37], v[164:167], v[206:209], v[34:37]
	v_mfma_f32_16x16x32_bf16 v[22:25], v[156:159], v[214:217], v[22:25]
	v_mfma_f32_16x16x32_bf16 v[18:21], v[164:167], v[214:217], v[18:21]
	s_setprio 0
	s_setprio 1
	v_mfma_f32_16x16x32_bf16 v[46:49], v[168:171], v[184:187], v[46:49]
	v_mfma_f32_16x16x32_bf16 v[42:45], v[176:179], v[184:187], v[42:45]
	v_mfma_f32_16x16x32_bf16 v[30:33], v[168:171], v[192:195], v[30:33]
	v_mfma_f32_16x16x32_bf16 v[26:29], v[176:179], v[192:195], v[26:29]
	v_mfma_f32_16x16x32_bf16 v[14:17], v[168:171], v[200:203], v[14:17]
	v_mfma_f32_16x16x32_bf16 v[10:13], v[176:179], v[200:203], v[10:13]
	v_mfma_f32_16x16x32_bf16 v[6:9], v[168:171], v[210:213], v[6:9]
	v_mfma_f32_16x16x32_bf16 v[2:5], v[176:179], v[210:213], v[2:5]
	v_mfma_f32_16x16x32_bf16 v[46:49], v[172:175], v[188:191], v[46:49]
	v_mfma_f32_16x16x32_bf16 v[42:45], v[180:183], v[188:191], v[42:45]
	v_mfma_f32_16x16x32_bf16 v[30:33], v[172:175], v[196:199], v[30:33]
	v_mfma_f32_16x16x32_bf16 v[26:29], v[180:183], v[196:199], v[26:29]
	v_mfma_f32_16x16x32_bf16 v[14:17], v[172:175], v[206:209], v[14:17]
	v_mfma_f32_16x16x32_bf16 v[10:13], v[180:183], v[206:209], v[10:13]
	v_mfma_f32_16x16x32_bf16 v[6:9], v[172:175], v[214:217], v[6:9]
	v_mfma_f32_16x16x32_bf16 v[2:5], v[180:183], v[214:217], v[2:5]
	s_setprio 0
	s_barrier
	s_add_i32 s68, s68, 2
	s_cmp_gt_u32 s68, 5
	s_mov_b64 s[42:43], s[44:45]

.LBB0_476:
	s_add_u32 s22, s2, s49
	s_addc_u32 s23, s3, s29
	s_and_b64 s[26:27], s[20:21], exec
	s_cselect_b32 s63, s23, s37
	s_cselect_b32 s64, s22, s36
	s_add_u32 s26, s16, s12
	s_addc_u32 s27, s17, s13
	s_and_b64 s[42:43], s[20:21], exec
	s_cselect_b32 s65, s27, s39
	s_cselect_b32 s66, s26, s38
	s_add_u32 s36, s36, 0x20080
	s_addc_u32 s37, s37, 0
	s_add_u32 s67, s38, 0x100
	s_addc_u32 s68, s39, 0
	s_mov_b32 s69, -2
	ds_read_b128 v[148:151], v144
	ds_read_b128 v[152:155], v144 offset:1024
	ds_read_b128 v[156:159], v144 offset:2048
	ds_read_b128 v[160:163], v144 offset:3072
	ds_read_b128 v[164:167], v145
	ds_read_b128 v[168:171], v145 offset:1024
	ds_read_b128 v[172:175], v145 offset:2048
	ds_read_b128 v[176:179], v145 offset:3072
	s_add_u32 s38, s36, 0xfffe0080
	s_addc_u32 s39, s37, -1
	s_cmp_eq_u32 s69, 4
	s_cselect_b32 s43, s63, s39
	s_cselect_b32 s42, s64, s38
	s_cselect_b32 s39, s65, s68
	s_cselect_b32 s38, s66, s67
	v_lshl_add_u64 v[214:215], s[36:37], 0, v[138:139]
	s_add_i32 m0, s19, 0xc000
	ds_read_b128 v[180:183], v146
	ds_read_b128 v[184:187], v146 offset:1024
	ds_read_b128 v[188:191], v146 offset:2048
	ds_read_b128 v[192:195], v146 offset:3072
	ds_read_b128 v[196:199], v146 offset:4096
	ds_read_b128 v[200:203], v146 offset:5120
	ds_read_b128 v[206:209], v146 offset:6144
	ds_read_b128 v[210:213], v146 offset:7168
	global_load_lds_dwordx4 v[214:215], off
	v_lshl_add_u64 v[214:215], s[36:37], 0, v[140:141]
	s_add_i32 m0, s19, 0xe000
	s_nop 0
	global_load_lds_dwordx4 v[214:215], off
	s_waitcnt vmcnt(8)
	s_waitcnt lgkmcnt(0)
	s_barrier
	s_setprio 1
	s_waitcnt lgkmcnt(0)
	v_mfma_f32_16x16x32_bf16 v[126:129], v[148:151], v[180:183], 0
	v_mfma_f32_16x16x32_bf16 v[122:125], v[156:159], v[180:183], 0
	v_mfma_f32_16x16x32_bf16 v[118:121], v[148:151], v[188:191], 0
	v_mfma_f32_16x16x32_bf16 v[114:117], v[156:159], v[188:191], 0
	v_mfma_f32_16x16x32_bf16 v[102:105], v[148:151], v[196:199], 0
	v_mfma_f32_16x16x32_bf16 v[98:101], v[156:159], v[196:199], 0
	v_mfma_f32_16x16x32_bf16 v[86:89], v[148:151], v[206:209], 0
	v_mfma_f32_16x16x32_bf16 v[82:85], v[156:159], v[206:209], 0
	v_mfma_f32_16x16x32_bf16 v[126:129], v[152:155], v[184:187], v[126:129]
	v_mfma_f32_16x16x32_bf16 v[122:125], v[160:163], v[184:187], v[122:125]
	v_mfma_f32_16x16x32_bf16 v[118:121], v[152:155], v[192:195], v[118:121]
	v_mfma_f32_16x16x32_bf16 v[114:117], v[160:163], v[192:195], v[114:117]
	v_mfma_f32_16x16x32_bf16 v[102:105], v[152:155], v[200:203], v[102:105]
	v_mfma_f32_16x16x32_bf16 v[98:101], v[160:163], v[200:203], v[98:101]
	v_mfma_f32_16x16x32_bf16 v[86:89], v[152:155], v[210:213], v[86:89]
	v_mfma_f32_16x16x32_bf16 v[82:85], v[160:163], v[210:213], v[82:85]
	s_setprio 0
	s_setprio 1
	v_mfma_f32_16x16x32_bf16 v[110:113], v[164:167], v[180:183], 0
	v_mfma_f32_16x16x32_bf16 v[106:109], v[172:175], v[180:183], 0
	v_mfma_f32_16x16x32_bf16 v[94:97], v[164:167], v[188:191], 0
	v_mfma_f32_16x16x32_bf16 v[90:93], v[172:175], v[188:191], 0
	v_mfma_f32_16x16x32_bf16 v[78:81], v[164:167], v[196:199], 0
	v_mfma_f32_16x16x32_bf16 v[74:77], v[172:175], v[196:199], 0
	v_mfma_f32_16x16x32_bf16 v[70:73], v[164:167], v[206:209], 0
	v_mfma_f32_16x16x32_bf16 v[66:69], v[172:175], v[206:209], 0
	v_mfma_f32_16x16x32_bf16 v[110:113], v[168:171], v[184:187], v[110:113]
	v_mfma_f32_16x16x32_bf16 v[106:109], v[176:179], v[184:187], v[106:109]
	v_mfma_f32_16x16x32_bf16 v[94:97], v[168:171], v[192:195], v[94:97]
	v_mfma_f32_16x16x32_bf16 v[90:93], v[176:179], v[192:195], v[90:93]
	v_mfma_f32_16x16x32_bf16 v[78:81], v[168:171], v[200:203], v[78:81]
	v_mfma_f32_16x16x32_bf16 v[74:77], v[176:179], v[200:203], v[74:77]
	v_mfma_f32_16x16x32_bf16 v[70:73], v[168:171], v[210:213], v[70:73]
	v_mfma_f32_16x16x32_bf16 v[66:69], v[176:179], v[210:213], v[66:69]
	s_setprio 0
	s_barrier
	s_add_i32 s70, s35, s18
	v_lshl_add_u64 v[214:215], s[38:39], 0, v[134:135]
	s_mov_b32 m0, s70
	ds_read_b128 v[180:183], v146 offset:16384
	ds_read_b128 v[184:187], v146 offset:17408
	ds_read_b128 v[188:191], v146 offset:18432
	ds_read_b128 v[192:195], v146 offset:19456
	ds_read_b128 v[196:199], v146 offset:20480
	ds_read_b128 v[200:203], v146 offset:21504
	ds_read_b128 v[206:209], v146 offset:22528
	ds_read_b128 v[210:213], v146 offset:23552
	global_load_lds_dwordx4 v[214:215], off
	s_add_i32 m0, s70, 0x2000
	s_add_u32 s70, s38, 0x200000
	v_lshl_add_u64 v[216:217], s[38:39], 0, v[130:131]
	s_addc_u32 s71, s39, 0
	s_add_i32 s72, s44, s18
	global_load_lds_dwordx4 v[216:217], off
	v_lshl_add_u64 v[218:219], s[70:71], 0, v[134:135]
	s_mov_b32 m0, s72
	v_lshl_add_u64 v[220:221], s[42:43], 0, v[132:133]
	global_load_lds_dwordx4 v[218:219], off
	v_lshl_add_u64 v[218:219], s[70:71], 0, v[130:131]
	s_add_i32 m0, s72, 0x2000
	s_nop 0
	global_load_lds_dwordx4 v[218:219], off
	v_lshl_add_u64 v[218:219], s[42:43], 0, v[136:137]
	s_mov_b32 m0, s19
	s_nop 0
	global_load_lds_dwordx4 v[218:219], off
	s_mov_b32 m0, s24
	s_nop 0
	global_load_lds_dwordx4 v[220:221], off
	s_waitcnt vmcnt(8)
	s_waitcnt lgkmcnt(0)
	s_barrier
	s_setprio 1
	s_waitcnt lgkmcnt(0)
	v_mfma_f32_16x16x32_bf16 v[62:65], v[148:151], v[180:183], 0
	v_mfma_f32_16x16x32_bf16 v[58:61], v[156:159], v[180:183], 0
	v_mfma_f32_16x16x32_bf16 v[54:57], v[148:151], v[188:191], 0
	v_mfma_f32_16x16x32_bf16 v[50:53], v[156:159], v[188:191], 0
	v_mfma_f32_16x16x32_bf16 v[38:41], v[148:151], v[196:199], 0
	v_mfma_f32_16x16x32_bf16 v[34:37], v[156:159], v[196:199], 0
	v_mfma_f32_16x16x32_bf16 v[22:25], v[148:151], v[206:209], 0
	v_mfma_f32_16x16x32_bf16 v[18:21], v[156:159], v[206:209], 0
	v_mfma_f32_16x16x32_bf16 v[62:65], v[152:155], v[184:187], v[62:65]
	v_mfma_f32_16x16x32_bf16 v[58:61], v[160:163], v[184:187], v[58:61]
	v_mfma_f32_16x16x32_bf16 v[54:57], v[152:155], v[192:195], v[54:57]
	v_mfma_f32_16x16x32_bf16 v[50:53], v[160:163], v[192:195], v[50:53]
	v_mfma_f32_16x16x32_bf16 v[38:41], v[152:155], v[200:203], v[38:41]
	v_mfma_f32_16x16x32_bf16 v[34:37], v[160:163], v[200:203], v[34:37]
	v_mfma_f32_16x16x32_bf16 v[22:25], v[152:155], v[210:213], v[22:25]
	v_mfma_f32_16x16x32_bf16 v[18:21], v[160:163], v[210:213], v[18:21]
	s_setprio 0
	s_setprio 1
	v_mfma_f32_16x16x32_bf16 v[46:49], v[164:167], v[180:183], 0
	v_mfma_f32_16x16x32_bf16 v[42:45], v[172:175], v[180:183], 0
	v_mfma_f32_16x16x32_bf16 v[30:33], v[164:167], v[188:191], 0
	v_mfma_f32_16x16x32_bf16 v[26:29], v[172:175], v[188:191], 0
	v_mfma_f32_16x16x32_bf16 v[14:17], v[164:167], v[196:199], 0
	v_mfma_f32_16x16x32_bf16 v[10:13], v[172:175], v[196:199], 0
	v_mfma_f32_16x16x32_bf16 v[6:9], v[164:167], v[206:209], 0
	v_mfma_f32_16x16x32_bf16 v[2:5], v[172:175], v[206:209], 0
	v_mfma_f32_16x16x32_bf16 v[46:49], v[168:171], v[184:187], v[46:49]
	v_mfma_f32_16x16x32_bf16 v[42:45], v[176:179], v[184:187], v[42:45]
	v_mfma_f32_16x16x32_bf16 v[30:33], v[168:171], v[192:195], v[30:33]
	v_mfma_f32_16x16x32_bf16 v[26:29], v[176:179], v[192:195], v[26:29]
	v_mfma_f32_16x16x32_bf16 v[14:17], v[168:171], v[200:203], v[14:17]
	v_mfma_f32_16x16x32_bf16 v[10:13], v[176:179], v[200:203], v[10:13]
	v_mfma_f32_16x16x32_bf16 v[6:9], v[168:171], v[210:213], v[6:9]
	v_mfma_f32_16x16x32_bf16 v[2:5], v[176:179], v[210:213], v[2:5]
	s_setprio 0
	s_barrier
	s_add_i32 s70, 0, 0x18000
	v_add_u32_e32 v147, s70, v143
	s_add_i32 s71, 0, 0x1c000
	ds_read_b128 v[148:151], v147
	ds_read_b128 v[152:155], v147 offset:1024
	ds_read_b128 v[156:159], v147 offset:2048
	ds_read_b128 v[160:163], v147 offset:3072
	v_add_u32_e32 v147, s71, v143
	ds_read_b128 v[164:167], v147
	ds_read_b128 v[168:171], v147 offset:1024
	ds_read_b128 v[172:175], v147 offset:2048
	ds_read_b128 v[176:179], v147 offset:3072
	s_add_u32 s42, s42, 0x20000
	s_addc_u32 s43, s43, 0
	s_mov_b32 m0, s25
	v_lshl_add_u64 v[222:223], s[42:43], 0, v[136:137]
	ds_read_b128 v[180:183], v146 offset:32768
	ds_read_b128 v[184:187], v146 offset:33792
	ds_read_b128 v[188:191], v146 offset:34816
	ds_read_b128 v[192:195], v146 offset:35840
	ds_read_b128 v[196:199], v146 offset:36864
	ds_read_b128 v[200:203], v146 offset:37888
	ds_read_b128 v[206:209], v146 offset:38912
	ds_read_b128 v[210:213], v146 offset:39936
	global_load_lds_dwordx4 v[222:223], off
	v_lshl_add_u64 v[222:223], s[42:43], 0, v[132:133]
	s_mov_b32 m0, s28
	s_nop 0
	global_load_lds_dwordx4 v[222:223], off
	s_waitcnt vmcnt(8)
	s_waitcnt lgkmcnt(0)
	s_barrier
	s_setprio 1
	s_waitcnt lgkmcnt(0)
	v_mfma_f32_16x16x32_bf16 v[126:129], v[148:151], v[180:183], v[126:129]
	v_mfma_f32_16x16x32_bf16 v[122:125], v[156:159], v[180:183], v[122:125]
	v_mfma_f32_16x16x32_bf16 v[118:121], v[148:151], v[188:191], v[118:121]
	v_mfma_f32_16x16x32_bf16 v[114:117], v[156:159], v[188:191], v[114:117]
	v_mfma_f32_16x16x32_bf16 v[102:105], v[148:151], v[196:199], v[102:105]
	v_mfma_f32_16x16x32_bf16 v[98:101], v[156:159], v[196:199], v[98:101]
	v_mfma_f32_16x16x32_bf16 v[86:89], v[148:151], v[206:209], v[86:89]
	v_mfma_f32_16x16x32_bf16 v[82:85], v[156:159], v[206:209], v[82:85]
	v_mfma_f32_16x16x32_bf16 v[126:129], v[152:155], v[184:187], v[126:129]
	v_mfma_f32_16x16x32_bf16 v[122:125], v[160:163], v[184:187], v[122:125]
	v_mfma_f32_16x16x32_bf16 v[118:121], v[152:155], v[192:195], v[118:121]
	v_mfma_f32_16x16x32_bf16 v[114:117], v[160:163], v[192:195], v[114:117]
	v_mfma_f32_16x16x32_bf16 v[102:105], v[152:155], v[200:203], v[102:105]
	v_mfma_f32_16x16x32_bf16 v[98:101], v[160:163], v[200:203], v[98:101]
	v_mfma_f32_16x16x32_bf16 v[86:89], v[152:155], v[210:213], v[86:89]
	v_mfma_f32_16x16x32_bf16 v[82:85], v[160:163], v[210:213], v[82:85]
	s_setprio 0
	s_setprio 1
	v_mfma_f32_16x16x32_bf16 v[110:113], v[164:167], v[180:183], v[110:113]
	v_mfma_f32_16x16x32_bf16 v[106:109], v[172:175], v[180:183], v[106:109]
	v_mfma_f32_16x16x32_bf16 v[94:97], v[164:167], v[188:191], v[94:97]
	v_mfma_f32_16x16x32_bf16 v[90:93], v[172:175], v[188:191], v[90:93]
	v_mfma_f32_16x16x32_bf16 v[78:81], v[164:167], v[196:199], v[78:81]
	v_mfma_f32_16x16x32_bf16 v[74:77], v[172:175], v[196:199], v[74:77]
	v_mfma_f32_16x16x32_bf16 v[70:73], v[164:167], v[206:209], v[70:73]
	v_mfma_f32_16x16x32_bf16 v[66:69], v[172:175], v[206:209], v[66:69]
	v_mfma_f32_16x16x32_bf16 v[110:113], v[168:171], v[184:187], v[110:113]
	v_mfma_f32_16x16x32_bf16 v[106:109], v[176:179], v[184:187], v[106:109]
	v_mfma_f32_16x16x32_bf16 v[94:97], v[168:171], v[192:195], v[94:97]
	v_mfma_f32_16x16x32_bf16 v[90:93], v[176:179], v[192:195], v[90:93]
	v_mfma_f32_16x16x32_bf16 v[78:81], v[168:171], v[200:203], v[78:81]
	v_mfma_f32_16x16x32_bf16 v[74:77], v[176:179], v[200:203], v[74:77]
	v_mfma_f32_16x16x32_bf16 v[70:73], v[168:171], v[210:213], v[70:73]
	v_mfma_f32_16x16x32_bf16 v[66:69], v[176:179], v[210:213], v[66:69]
	s_setprio 0
	s_barrier
	s_add_i32 s42, s70, s18
	v_lshl_add_u64 v[214:215], v[214:215], 0, s[8:9]
	s_mov_b32 m0, s42
	ds_read_b128 v[180:183], v146 offset:49152
	ds_read_b128 v[184:187], v146 offset:50176
	ds_read_b128 v[188:191], v146 offset:51200
	ds_read_b128 v[192:195], v146 offset:52224
	ds_read_b128 v[196:199], v146 offset:53248
	ds_read_b128 v[200:203], v146 offset:54272
	ds_read_b128 v[206:209], v146 offset:55296
	ds_read_b128 v[210:213], v146 offset:56320
	global_load_lds_dwordx4 v[214:215], off
	s_add_i32 m0, s42, 0x2000
	s_add_u32 s38, s38, 0x200080
	v_lshl_add_u64 v[214:215], v[216:217], 0, s[8:9]
	s_addc_u32 s39, s39, 0
	s_add_i32 s42, s71, s18
	global_load_lds_dwordx4 v[214:215], off
	v_lshl_add_u64 v[214:215], s[38:39], 0, v[134:135]
	s_mov_b32 m0, s42
	s_nop 0
	global_load_lds_dwordx4 v[214:215], off
	v_lshl_add_u64 v[214:215], s[38:39], 0, v[130:131]
	s_add_i32 m0, s42, 0x2000
	s_nop 0
	global_load_lds_dwordx4 v[214:215], off
	v_lshl_add_u64 v[214:215], v[218:219], 0, s[8:9]
	s_mov_b32 m0, s33
	s_nop 0
	global_load_lds_dwordx4 v[214:215], off
	v_lshl_add_u64 v[214:215], v[220:221], 0, s[8:9]
	s_mov_b32 m0, s34
	s_nop 0
	global_load_lds_dwordx4 v[214:215], off
	s_waitcnt vmcnt(8)
	s_waitcnt lgkmcnt(0)
	s_barrier
	s_setprio 1
	s_waitcnt lgkmcnt(0)
	v_mfma_f32_16x16x32_bf16 v[62:65], v[148:151], v[180:183], v[62:65]
	v_mfma_f32_16x16x32_bf16 v[58:61], v[156:159], v[180:183], v[58:61]
	v_mfma_f32_16x16x32_bf16 v[54:57], v[148:151], v[188:191], v[54:57]
	v_mfma_f32_16x16x32_bf16 v[50:53], v[156:159], v[188:191], v[50:53]
	v_mfma_f32_16x16x32_bf16 v[38:41], v[148:151], v[196:199], v[38:41]
	v_mfma_f32_16x16x32_bf16 v[34:37], v[156:159], v[196:199], v[34:37]
	v_mfma_f32_16x16x32_bf16 v[22:25], v[148:151], v[206:209], v[22:25]
	v_mfma_f32_16x16x32_bf16 v[18:21], v[156:159], v[206:209], v[18:21]
	v_mfma_f32_16x16x32_bf16 v[62:65], v[152:155], v[184:187], v[62:65]
	v_mfma_f32_16x16x32_bf16 v[58:61], v[160:163], v[184:187], v[58:61]
	v_mfma_f32_16x16x32_bf16 v[54:57], v[152:155], v[192:195], v[54:57]
	v_mfma_f32_16x16x32_bf16 v[50:53], v[160:163], v[192:195], v[50:53]
	v_mfma_f32_16x16x32_bf16 v[38:41], v[152:155], v[200:203], v[38:41]
	v_mfma_f32_16x16x32_bf16 v[34:37], v[160:163], v[200:203], v[34:37]
	v_mfma_f32_16x16x32_bf16 v[22:25], v[152:155], v[210:213], v[22:25]
	v_mfma_f32_16x16x32_bf16 v[18:21], v[160:163], v[210:213], v[18:21]
	s_setprio 0
	s_setprio 1
	v_mfma_f32_16x16x32_bf16 v[46:49], v[164:167], v[180:183], v[46:49]
	v_mfma_f32_16x16x32_bf16 v[42:45], v[172:175], v[180:183], v[42:45]
	v_mfma_f32_16x16x32_bf16 v[30:33], v[164:167], v[188:191], v[30:33]
	v_mfma_f32_16x16x32_bf16 v[26:29], v[172:175], v[188:191], v[26:29]
	v_mfma_f32_16x16x32_bf16 v[14:17], v[164:167], v[196:199], v[14:17]
	v_mfma_f32_16x16x32_bf16 v[10:13], v[172:175], v[196:199], v[10:13]
	v_mfma_f32_16x16x32_bf16 v[6:9], v[164:167], v[206:209], v[6:9]
	v_mfma_f32_16x16x32_bf16 v[2:5], v[172:175], v[206:209], v[2:5]
	v_mfma_f32_16x16x32_bf16 v[46:49], v[168:171], v[184:187], v[46:49]
	v_mfma_f32_16x16x32_bf16 v[42:45], v[176:179], v[184:187], v[42:45]
	v_mfma_f32_16x16x32_bf16 v[30:33], v[168:171], v[192:195], v[30:33]
	v_mfma_f32_16x16x32_bf16 v[26:29], v[176:179], v[192:195], v[26:29]
	v_mfma_f32_16x16x32_bf16 v[14:17], v[168:171], v[200:203], v[14:17]
	v_mfma_f32_16x16x32_bf16 v[10:13], v[176:179], v[200:203], v[10:13]
	v_mfma_f32_16x16x32_bf16 v[6:9], v[168:171], v[210:213], v[6:9]
	v_mfma_f32_16x16x32_bf16 v[2:5], v[176:179], v[210:213], v[2:5]
	s_setprio 0
	s_barrier
	s_add_i32 s69, s69, 2
	s_add_u32 s36, s36, 0x100
	s_addc_u32 s37, s37, 0
	s_add_u32 s67, s67, 0x100
	s_addc_u32 s68, s68, 0
	s_cmp_gt_u32 s69, 5

.LBB0_565:
	v_readlane_b32 s62, v249, 27
	v_readlane_b32 s63, v249, 28
	s_add_u32 s72, s62, s68
	s_addc_u32 s73, s63, s69
	s_and_b64 s[62:63], s[70:71], exec
	s_cselect_b32 s31, s73, s77
	s_cselect_b32 s33, s72, s76
	s_add_u32 s74, s35, s66
	s_addc_u32 s75, s85, s67
	s_and_b64 s[62:63], s[70:71], exec
	s_cselect_b32 s34, s75, s79
	s_cselect_b32 s39, s74, s78
	s_add_i32 s45, s7, -2
	s_add_u32 s76, s76, 0x40080
	s_addc_u32 s77, s77, 0
	s_add_u32 s47, s78, 0x100
	s_addc_u32 s62, s79, 0
	s_mov_b32 s63, 0
	s_waitcnt vmcnt(0)
	ds_read_b128 v[114:117], v190
	ds_read_b128 v[118:121], v190 offset:1024
	ds_read_b128 v[122:125], v190 offset:2048
	ds_read_b128 v[126:129], v190 offset:3072
	ds_read_b128 v[146:149], v191
	ds_read_b128 v[150:153], v191 offset:1024
	ds_read_b128 v[154:157], v191 offset:2048
	ds_read_b128 v[158:161], v191 offset:3072
	s_add_i32 s82, s63, 2
	s_add_u32 s78, s76, 0xfffc0080
	s_addc_u32 s79, s77, -1
	s_cmp_eq_u32 s45, s63
	s_cselect_b32 s81, s31, s79
	s_cselect_b32 s80, s33, s78
	s_cselect_b32 s79, s34, s62
	s_cselect_b32 s78, s39, s47
	v_lshl_add_u64 v[186:187], s[76:77], 0, v[180:181]
	s_add_i32 m0, s87, 0xc000
	ds_read_b128 v[162:165], v192
	ds_read_b128 v[166:169], v192 offset:1024
	ds_read_b128 v[194:197], v192 offset:2048
	ds_read_b128 v[198:201], v192 offset:3072
	ds_read_b128 v[206:209], v192 offset:4096
	ds_read_b128 v[210:213], v192 offset:5120
	ds_read_b128 v[214:217], v192 offset:6144
	ds_read_b128 v[218:221], v192 offset:7168
	global_load_lds_dwordx4 v[186:187], off
	v_lshl_add_u64 v[186:187], s[76:77], 0, v[182:183]
	s_add_i32 m0, s87, 0xe000
	s_nop 0
	global_load_lds_dwordx4 v[186:187], off
	s_waitcnt vmcnt(8)
	s_waitcnt lgkmcnt(0)
	s_barrier
	s_setprio 1
	s_waitcnt lgkmcnt(0)
	v_mfma_f32_16x16x32_bf16 v[142:145], v[114:117], v[162:165], 0
	v_mfma_f32_16x16x32_bf16 v[138:141], v[122:125], v[162:165], 0
	v_mfma_f32_16x16x32_bf16 v[110:113], v[114:117], v[194:197], 0
	v_mfma_f32_16x16x32_bf16 v[106:109], v[122:125], v[194:197], 0
	v_mfma_f32_16x16x32_bf16 v[98:101], v[114:117], v[206:209], 0
	v_mfma_f32_16x16x32_bf16 v[90:93], v[122:125], v[206:209], 0
	v_mfma_f32_16x16x32_bf16 v[82:85], v[114:117], v[214:217], 0
	v_mfma_f32_16x16x32_bf16 v[74:77], v[122:125], v[214:217], 0
	v_mfma_f32_16x16x32_bf16 v[142:145], v[118:121], v[166:169], v[142:145]
	v_mfma_f32_16x16x32_bf16 v[138:141], v[126:129], v[166:169], v[138:141]
	v_mfma_f32_16x16x32_bf16 v[110:113], v[118:121], v[198:201], v[110:113]
	v_mfma_f32_16x16x32_bf16 v[106:109], v[126:129], v[198:201], v[106:109]
	v_mfma_f32_16x16x32_bf16 v[98:101], v[118:121], v[210:213], v[98:101]
	v_mfma_f32_16x16x32_bf16 v[90:93], v[126:129], v[210:213], v[90:93]
	v_mfma_f32_16x16x32_bf16 v[82:85], v[118:121], v[218:221], v[82:85]
	v_mfma_f32_16x16x32_bf16 v[74:77], v[126:129], v[218:221], v[74:77]
	s_setprio 0
	s_setprio 1
	v_mfma_f32_16x16x32_bf16 v[134:137], v[146:149], v[162:165], 0
	v_mfma_f32_16x16x32_bf16 v[130:133], v[154:157], v[162:165], 0
	v_mfma_f32_16x16x32_bf16 v[102:105], v[146:149], v[194:197], 0
	v_mfma_f32_16x16x32_bf16 v[94:97], v[154:157], v[194:197], 0
	v_mfma_f32_16x16x32_bf16 v[86:89], v[146:149], v[206:209], 0
	v_mfma_f32_16x16x32_bf16 v[78:81], v[154:157], v[206:209], 0
	v_mfma_f32_16x16x32_bf16 v[70:73], v[146:149], v[214:217], 0
	v_mfma_f32_16x16x32_bf16 v[66:69], v[154:157], v[214:217], 0
	v_mfma_f32_16x16x32_bf16 v[134:137], v[150:153], v[166:169], v[134:137]
	v_mfma_f32_16x16x32_bf16 v[130:133], v[158:161], v[166:169], v[130:133]
	v_mfma_f32_16x16x32_bf16 v[102:105], v[150:153], v[198:201], v[102:105]
	v_mfma_f32_16x16x32_bf16 v[94:97], v[158:161], v[198:201], v[94:97]
	v_mfma_f32_16x16x32_bf16 v[86:89], v[150:153], v[210:213], v[86:89]
	v_mfma_f32_16x16x32_bf16 v[78:81], v[158:161], v[210:213], v[78:81]
	v_mfma_f32_16x16x32_bf16 v[70:73], v[150:153], v[218:221], v[70:73]
	v_mfma_f32_16x16x32_bf16 v[66:69], v[158:161], v[218:221], v[66:69]
	s_setprio 0
	s_barrier
	s_add_i32 s63, s24, s86
	v_lshl_add_u64 v[186:187], s[78:79], 0, v[172:173]
	s_mov_b32 m0, s63
	ds_read_b128 v[162:165], v192 offset:16384
	ds_read_b128 v[166:169], v192 offset:17408
	ds_read_b128 v[194:197], v192 offset:18432
	ds_read_b128 v[198:201], v192 offset:19456
	ds_read_b128 v[206:209], v192 offset:20480
	ds_read_b128 v[210:213], v192 offset:21504
	ds_read_b128 v[214:217], v192 offset:22528
	ds_read_b128 v[218:221], v192 offset:23552
	global_load_lds_dwordx4 v[186:187], off
	s_add_i32 m0, s63, 0x2000
	s_add_u32 vcc_lo, s78, 0x40000
	v_lshl_add_u64 v[202:203], s[78:79], 0, v[176:177]
	s_addc_u32 vcc_hi, s79, 0
	s_add_i32 s63, s25, s86
	global_load_lds_dwordx4 v[202:203], off
	v_lshl_add_u64 v[222:223], vcc, 0, v[172:173]
	s_mov_b32 m0, s63
	v_lshl_add_u64 v[224:225], s[80:81], 0, v[174:175]
	global_load_lds_dwordx4 v[222:223], off
	v_lshl_add_u64 v[222:223], vcc, 0, v[176:177]
	s_add_i32 m0, s63, 0x2000
	s_nop 0
	global_load_lds_dwordx4 v[222:223], off
	v_lshl_add_u64 v[222:223], s[80:81], 0, v[170:171]
	s_mov_b32 m0, s87
	s_nop 0
	global_load_lds_dwordx4 v[222:223], off
	s_mov_b32 m0, s88
	s_nop 0
	global_load_lds_dwordx4 v[224:225], off
	s_waitcnt vmcnt(8)
	s_waitcnt lgkmcnt(0)
	s_barrier
	s_setprio 1
	s_waitcnt lgkmcnt(0)
	v_mfma_f32_16x16x32_bf16 v[62:65], v[114:117], v[162:165], 0
	v_mfma_f32_16x16x32_bf16 v[58:61], v[122:125], v[162:165], 0
	v_mfma_f32_16x16x32_bf16 v[50:53], v[114:117], v[194:197], 0
	v_mfma_f32_16x16x32_bf16 v[42:45], v[122:125], v[194:197], 0
	v_mfma_f32_16x16x32_bf16 v[34:37], v[114:117], v[206:209], 0
	v_mfma_f32_16x16x32_bf16 v[26:29], v[122:125], v[206:209], 0
	v_mfma_f32_16x16x32_bf16 v[18:21], v[114:117], v[214:217], 0
	v_mfma_f32_16x16x32_bf16 v[10:13], v[122:125], v[214:217], 0
	v_mfma_f32_16x16x32_bf16 v[62:65], v[118:121], v[166:169], v[62:65]
	v_mfma_f32_16x16x32_bf16 v[58:61], v[126:129], v[166:169], v[58:61]
	v_mfma_f32_16x16x32_bf16 v[50:53], v[118:121], v[198:201], v[50:53]
	v_mfma_f32_16x16x32_bf16 v[42:45], v[126:129], v[198:201], v[42:45]
	v_mfma_f32_16x16x32_bf16 v[34:37], v[118:121], v[210:213], v[34:37]
	v_mfma_f32_16x16x32_bf16 v[26:29], v[126:129], v[210:213], v[26:29]
	v_mfma_f32_16x16x32_bf16 v[18:21], v[118:121], v[218:221], v[18:21]
	v_mfma_f32_16x16x32_bf16 v[10:13], v[126:129], v[218:221], v[10:13]
	s_setprio 0
	s_setprio 1
	v_mfma_f32_16x16x32_bf16 v[54:57], v[146:149], v[162:165], 0
	v_mfma_f32_16x16x32_bf16 v[46:49], v[154:157], v[162:165], 0
	v_mfma_f32_16x16x32_bf16 v[38:41], v[146:149], v[194:197], 0
	v_mfma_f32_16x16x32_bf16 v[30:33], v[154:157], v[194:197], 0
	v_mfma_f32_16x16x32_bf16 v[22:25], v[146:149], v[206:209], 0
	v_mfma_f32_16x16x32_bf16 v[14:17], v[154:157], v[206:209], 0
	v_mfma_f32_16x16x32_bf16 v[6:9], v[146:149], v[214:217], 0
	v_mfma_f32_16x16x32_bf16 v[2:5], v[154:157], v[214:217], 0
	v_mfma_f32_16x16x32_bf16 v[54:57], v[150:153], v[166:169], v[54:57]
	v_mfma_f32_16x16x32_bf16 v[46:49], v[158:161], v[166:169], v[46:49]
	v_mfma_f32_16x16x32_bf16 v[38:41], v[150:153], v[198:201], v[38:41]
	v_mfma_f32_16x16x32_bf16 v[30:33], v[158:161], v[198:201], v[30:33]
	v_mfma_f32_16x16x32_bf16 v[22:25], v[150:153], v[210:213], v[22:25]
	v_mfma_f32_16x16x32_bf16 v[14:17], v[158:161], v[210:213], v[14:17]
	v_mfma_f32_16x16x32_bf16 v[6:9], v[150:153], v[218:221], v[6:9]
	v_mfma_f32_16x16x32_bf16 v[2:5], v[158:161], v[218:221], v[2:5]
	s_setprio 0
	s_barrier
	s_add_i32 s63, 0, 0x18000
	s_add_i32 s83, 0, 0x1c000
	v_add_u32_e32 v126, s63, v189
	v_add_u32_e32 v158, s83, v189
	ds_read_b128 v[114:117], v126
	ds_read_b128 v[118:121], v126 offset:1024
	ds_read_b128 v[122:125], v126 offset:2048
	ds_read_b128 v[126:129], v126 offset:3072
	ds_read_b128 v[146:149], v158
	ds_read_b128 v[150:153], v158 offset:1024
	ds_read_b128 v[154:157], v158 offset:2048
	ds_read_b128 v[158:161], v158 offset:3072
	s_add_u32 s80, s80, 0x40000
	s_addc_u32 s81, s81, 0
	s_mov_b32 m0, s89
	v_lshl_add_u64 v[226:227], s[80:81], 0, v[170:171]
	ds_read_b128 v[162:165], v192 offset:32768
	ds_read_b128 v[166:169], v192 offset:33792
	ds_read_b128 v[194:197], v192 offset:34816
	ds_read_b128 v[198:201], v192 offset:35840
	ds_read_b128 v[206:209], v192 offset:36864
	ds_read_b128 v[210:213], v192 offset:37888
	ds_read_b128 v[214:217], v192 offset:38912
	ds_read_b128 v[218:221], v192 offset:39936
	global_load_lds_dwordx4 v[226:227], off
	v_lshl_add_u64 v[226:227], s[80:81], 0, v[174:175]
	s_mov_b32 m0, s90
	s_nop 0
	global_load_lds_dwordx4 v[226:227], off
	s_waitcnt vmcnt(8)
	s_waitcnt lgkmcnt(0)
	s_barrier
	s_setprio 1
	s_waitcnt lgkmcnt(0)
	v_mfma_f32_16x16x32_bf16 v[142:145], v[114:117], v[162:165], v[142:145]
	v_mfma_f32_16x16x32_bf16 v[138:141], v[122:125], v[162:165], v[138:141]
	v_mfma_f32_16x16x32_bf16 v[110:113], v[114:117], v[194:197], v[110:113]
	v_mfma_f32_16x16x32_bf16 v[106:109], v[122:125], v[194:197], v[106:109]
	v_mfma_f32_16x16x32_bf16 v[98:101], v[114:117], v[206:209], v[98:101]
	v_mfma_f32_16x16x32_bf16 v[90:93], v[122:125], v[206:209], v[90:93]
	v_mfma_f32_16x16x32_bf16 v[82:85], v[114:117], v[214:217], v[82:85]
	v_mfma_f32_16x16x32_bf16 v[74:77], v[122:125], v[214:217], v[74:77]
	v_mfma_f32_16x16x32_bf16 v[142:145], v[118:121], v[166:169], v[142:145]
	v_mfma_f32_16x16x32_bf16 v[138:141], v[126:129], v[166:169], v[138:141]
	v_mfma_f32_16x16x32_bf16 v[110:113], v[118:121], v[198:201], v[110:113]
	v_mfma_f32_16x16x32_bf16 v[106:109], v[126:129], v[198:201], v[106:109]
	v_mfma_f32_16x16x32_bf16 v[98:101], v[118:121], v[210:213], v[98:101]
	v_mfma_f32_16x16x32_bf16 v[90:93], v[126:129], v[210:213], v[90:93]
	v_mfma_f32_16x16x32_bf16 v[82:85], v[118:121], v[218:221], v[82:85]
	v_mfma_f32_16x16x32_bf16 v[74:77], v[126:129], v[218:221], v[74:77]
	s_setprio 0
	s_setprio 1
	v_mfma_f32_16x16x32_bf16 v[134:137], v[146:149], v[162:165], v[134:137]
	v_mfma_f32_16x16x32_bf16 v[130:133], v[154:157], v[162:165], v[130:133]
	v_mfma_f32_16x16x32_bf16 v[102:105], v[146:149], v[194:197], v[102:105]
	v_mfma_f32_16x16x32_bf16 v[94:97], v[154:157], v[194:197], v[94:97]
	v_mfma_f32_16x16x32_bf16 v[86:89], v[146:149], v[206:209], v[86:89]
	v_mfma_f32_16x16x32_bf16 v[78:81], v[154:157], v[206:209], v[78:81]
	v_mfma_f32_16x16x32_bf16 v[70:73], v[146:149], v[214:217], v[70:73]
	v_mfma_f32_16x16x32_bf16 v[66:69], v[154:157], v[214:217], v[66:69]
	v_mfma_f32_16x16x32_bf16 v[134:137], v[150:153], v[166:169], v[134:137]
	v_mfma_f32_16x16x32_bf16 v[130:133], v[158:161], v[166:169], v[130:133]
	v_mfma_f32_16x16x32_bf16 v[102:105], v[150:153], v[198:201], v[102:105]
	v_mfma_f32_16x16x32_bf16 v[94:97], v[158:161], v[198:201], v[94:97]
	v_mfma_f32_16x16x32_bf16 v[86:89], v[150:153], v[210:213], v[86:89]
	v_mfma_f32_16x16x32_bf16 v[78:81], v[158:161], v[210:213], v[78:81]
	v_mfma_f32_16x16x32_bf16 v[70:73], v[150:153], v[218:221], v[70:73]
	v_mfma_f32_16x16x32_bf16 v[66:69], v[158:161], v[218:221], v[66:69]
	s_setprio 0
	s_barrier
	s_add_i32 s63, s63, s86
	v_lshl_add_u64 v[186:187], v[186:187], 0, s[22:23]
	s_mov_b32 m0, s63
	ds_read_b128 v[162:165], v192 offset:49152
	ds_read_b128 v[166:169], v192 offset:50176
	ds_read_b128 v[194:197], v192 offset:51200
	ds_read_b128 v[198:201], v192 offset:52224
	ds_read_b128 v[206:209], v192 offset:53248
	ds_read_b128 v[210:213], v192 offset:54272
	ds_read_b128 v[214:217], v192 offset:55296
	ds_read_b128 v[218:221], v192 offset:56320
	global_load_lds_dwordx4 v[186:187], off
	s_add_i32 m0, s63, 0x2000
	s_add_u32 s78, s78, 0x40080
	v_lshl_add_u64 v[186:187], v[202:203], 0, s[22:23]
	s_addc_u32 s79, s79, 0
	s_add_i32 s63, s83, s86
	global_load_lds_dwordx4 v[186:187], off
	v_lshl_add_u64 v[186:187], s[78:79], 0, v[172:173]
	s_mov_b32 m0, s63
	s_nop 0
	global_load_lds_dwordx4 v[186:187], off
	v_lshl_add_u64 v[186:187], s[78:79], 0, v[176:177]
	s_add_i32 m0, s63, 0x2000
	s_nop 0
	global_load_lds_dwordx4 v[186:187], off
	v_lshl_add_u64 v[186:187], v[222:223], 0, s[22:23]
	s_mov_b32 m0, s95
	s_nop 0
	global_load_lds_dwordx4 v[186:187], off
	v_lshl_add_u64 v[186:187], v[224:225], 0, s[22:23]
	s_mov_b32 m0, s96
	s_nop 0
	global_load_lds_dwordx4 v[186:187], off
	s_waitcnt vmcnt(8)
	s_waitcnt lgkmcnt(0)
	s_barrier
	s_setprio 1
	s_waitcnt lgkmcnt(0)
	v_mfma_f32_16x16x32_bf16 v[62:65], v[114:117], v[162:165], v[62:65]
	v_mfma_f32_16x16x32_bf16 v[58:61], v[122:125], v[162:165], v[58:61]
	v_mfma_f32_16x16x32_bf16 v[50:53], v[114:117], v[194:197], v[50:53]
	v_mfma_f32_16x16x32_bf16 v[42:45], v[122:125], v[194:197], v[42:45]
	v_mfma_f32_16x16x32_bf16 v[34:37], v[114:117], v[206:209], v[34:37]
	v_mfma_f32_16x16x32_bf16 v[26:29], v[122:125], v[206:209], v[26:29]
	v_mfma_f32_16x16x32_bf16 v[18:21], v[114:117], v[214:217], v[18:21]
	v_mfma_f32_16x16x32_bf16 v[10:13], v[122:125], v[214:217], v[10:13]
	v_mfma_f32_16x16x32_bf16 v[62:65], v[118:121], v[166:169], v[62:65]
	v_mfma_f32_16x16x32_bf16 v[58:61], v[126:129], v[166:169], v[58:61]
	v_mfma_f32_16x16x32_bf16 v[50:53], v[118:121], v[198:201], v[50:53]
	v_mfma_f32_16x16x32_bf16 v[42:45], v[126:129], v[198:201], v[42:45]
	v_mfma_f32_16x16x32_bf16 v[34:37], v[118:121], v[210:213], v[34:37]
	v_mfma_f32_16x16x32_bf16 v[26:29], v[126:129], v[210:213], v[26:29]
	v_mfma_f32_16x16x32_bf16 v[18:21], v[118:121], v[218:221], v[18:21]
	v_mfma_f32_16x16x32_bf16 v[10:13], v[126:129], v[218:221], v[10:13]
	s_setprio 0
	s_setprio 1
	v_mfma_f32_16x16x32_bf16 v[54:57], v[146:149], v[162:165], v[54:57]
	v_mfma_f32_16x16x32_bf16 v[46:49], v[154:157], v[162:165], v[46:49]
	v_mfma_f32_16x16x32_bf16 v[38:41], v[146:149], v[194:197], v[38:41]
	v_mfma_f32_16x16x32_bf16 v[30:33], v[154:157], v[194:197], v[30:33]
	v_mfma_f32_16x16x32_bf16 v[22:25], v[146:149], v[206:209], v[22:25]
	v_mfma_f32_16x16x32_bf16 v[14:17], v[154:157], v[206:209], v[14:17]
	v_mfma_f32_16x16x32_bf16 v[6:9], v[146:149], v[214:217], v[6:9]
	v_mfma_f32_16x16x32_bf16 v[2:5], v[154:157], v[214:217], v[2:5]
	v_mfma_f32_16x16x32_bf16 v[54:57], v[150:153], v[166:169], v[54:57]
	v_mfma_f32_16x16x32_bf16 v[46:49], v[158:161], v[166:169], v[46:49]
	v_mfma_f32_16x16x32_bf16 v[38:41], v[150:153], v[198:201], v[38:41]
	v_mfma_f32_16x16x32_bf16 v[30:33], v[158:161], v[198:201], v[30:33]
	v_mfma_f32_16x16x32_bf16 v[22:25], v[150:153], v[210:213], v[22:25]
	v_mfma_f32_16x16x32_bf16 v[14:17], v[158:161], v[210:213], v[14:17]
	v_mfma_f32_16x16x32_bf16 v[6:9], v[150:153], v[218:221], v[6:9]
	v_mfma_f32_16x16x32_bf16 v[2:5], v[158:161], v[218:221], v[2:5]
	s_setprio 0
	s_barrier
	s_add_u32 s76, s76, 0x100
	s_addc_u32 s77, s77, 0
	s_add_u32 s47, s47, 0x100
	s_addc_u32 s62, s62, 0
	s_cmp_ge_i32 s82, s7
	s_mov_b32 s63, s82

.LBB0_744:
	s_add_u32 s36, s96, s22
	s_addc_u32 s37, s97, s23
	s_and_b64 s[14:15], s[4:5], exec
	s_cselect_b32 s14, s37, s43
	s_cselect_b32 s15, s36, s42
	s_add_u32 s38, s2, s26
	s_addc_u32 s39, s3, s27
	s_and_b64 s[46:47], s[4:5], exec
	s_cselect_b32 s21, s39, s45
	s_cselect_b32 s65, s38, s44
	s_add_u32 s42, s42, 0x40080
	s_addc_u32 s43, s43, 0
	s_add_u32 s66, s44, 0x100
	s_addc_u32 s67, s45, 0
	s_mov_b32 s68, -2
	ds_read_b128 v[154:157], v150
	ds_read_b128 v[158:161], v150 offset:1024
	ds_read_b128 v[162:165], v150 offset:2048
	ds_read_b128 v[166:169], v150 offset:3072
	ds_read_b128 v[170:173], v151
	ds_read_b128 v[174:177], v151 offset:1024
	ds_read_b128 v[178:181], v151 offset:2048
	ds_read_b128 v[182:185], v151 offset:3072
	s_add_u32 s44, s42, 0xfffc0080
	s_addc_u32 s45, s43, -1
	s_cmp_eq_u32 s68, 12
	s_cselect_b32 s47, s14, s45
	s_cselect_b32 s46, s15, s44
	s_cselect_b32 s45, s21, s67
	s_cselect_b32 s44, s65, s66
	v_lshl_add_u64 v[146:147], s[42:43], 0, v[138:139]
	s_add_i32 m0, s19, 0xc000
	ds_read_b128 v[186:189], v152
	ds_read_b128 v[190:193], v152 offset:1024
	ds_read_b128 v[194:197], v152 offset:2048
	ds_read_b128 v[198:201], v152 offset:3072
	ds_read_b128 v[206:209], v152 offset:4096
	ds_read_b128 v[210:213], v152 offset:5120
	ds_read_b128 v[214:217], v152 offset:6144
	ds_read_b128 v[218:221], v152 offset:7168
	global_load_lds_dwordx4 v[146:147], off
	v_lshl_add_u64 v[146:147], s[42:43], 0, v[140:141]
	s_add_i32 m0, s19, 0xe000
	s_nop 0
	global_load_lds_dwordx4 v[146:147], off
	s_waitcnt vmcnt(8)
	s_waitcnt lgkmcnt(0)
	s_barrier
	s_setprio 1
	s_waitcnt lgkmcnt(0)
	v_mfma_f32_16x16x32_bf16 v[126:129], v[154:157], v[186:189], 0
	v_mfma_f32_16x16x32_bf16 v[122:125], v[162:165], v[186:189], 0
	v_mfma_f32_16x16x32_bf16 v[110:113], v[154:157], v[194:197], 0
	v_mfma_f32_16x16x32_bf16 v[106:109], v[162:165], v[194:197], 0
	v_mfma_f32_16x16x32_bf16 v[94:97], v[154:157], v[206:209], 0
	v_mfma_f32_16x16x32_bf16 v[90:93], v[162:165], v[206:209], 0
	v_mfma_f32_16x16x32_bf16 v[78:81], v[154:157], v[214:217], 0
	v_mfma_f32_16x16x32_bf16 v[74:77], v[162:165], v[214:217], 0
	v_mfma_f32_16x16x32_bf16 v[126:129], v[158:161], v[190:193], v[126:129]
	v_mfma_f32_16x16x32_bf16 v[122:125], v[166:169], v[190:193], v[122:125]
	v_mfma_f32_16x16x32_bf16 v[110:113], v[158:161], v[198:201], v[110:113]
	v_mfma_f32_16x16x32_bf16 v[106:109], v[166:169], v[198:201], v[106:109]
	v_mfma_f32_16x16x32_bf16 v[94:97], v[158:161], v[210:213], v[94:97]
	v_mfma_f32_16x16x32_bf16 v[90:93], v[166:169], v[210:213], v[90:93]
	v_mfma_f32_16x16x32_bf16 v[78:81], v[158:161], v[218:221], v[78:81]
	v_mfma_f32_16x16x32_bf16 v[74:77], v[166:169], v[218:221], v[74:77]
	s_setprio 0
	s_setprio 1
	v_mfma_f32_16x16x32_bf16 v[118:121], v[170:173], v[186:189], 0
	v_mfma_f32_16x16x32_bf16 v[114:117], v[178:181], v[186:189], 0
	v_mfma_f32_16x16x32_bf16 v[102:105], v[170:173], v[194:197], 0
	v_mfma_f32_16x16x32_bf16 v[98:101], v[178:181], v[194:197], 0
	v_mfma_f32_16x16x32_bf16 v[86:89], v[170:173], v[206:209], 0
	v_mfma_f32_16x16x32_bf16 v[82:85], v[178:181], v[206:209], 0
	v_mfma_f32_16x16x32_bf16 v[70:73], v[170:173], v[214:217], 0
	v_mfma_f32_16x16x32_bf16 v[66:69], v[178:181], v[214:217], 0
	v_mfma_f32_16x16x32_bf16 v[118:121], v[174:177], v[190:193], v[118:121]
	v_mfma_f32_16x16x32_bf16 v[114:117], v[182:185], v[190:193], v[114:117]
	v_mfma_f32_16x16x32_bf16 v[102:105], v[174:177], v[198:201], v[102:105]
	v_mfma_f32_16x16x32_bf16 v[98:101], v[182:185], v[198:201], v[98:101]
	v_mfma_f32_16x16x32_bf16 v[86:89], v[174:177], v[210:213], v[86:89]
	v_mfma_f32_16x16x32_bf16 v[82:85], v[182:185], v[210:213], v[82:85]
	v_mfma_f32_16x16x32_bf16 v[70:73], v[174:177], v[218:221], v[70:73]
	v_mfma_f32_16x16x32_bf16 v[66:69], v[182:185], v[218:221], v[66:69]
	s_setprio 0
	s_barrier
	s_add_i32 s69, s49, s16
	v_lshl_add_u64 v[146:147], s[44:45], 0, v[134:135]
	s_mov_b32 m0, s69
	ds_read_b128 v[186:189], v152 offset:16384
	ds_read_b128 v[190:193], v152 offset:17408
	ds_read_b128 v[194:197], v152 offset:18432
	ds_read_b128 v[198:201], v152 offset:19456
	ds_read_b128 v[206:209], v152 offset:20480
	ds_read_b128 v[210:213], v152 offset:21504
	ds_read_b128 v[214:217], v152 offset:22528
	ds_read_b128 v[218:221], v152 offset:23552
	global_load_lds_dwordx4 v[146:147], off
	s_add_i32 m0, s69, 0x2000
	s_add_u32 s70, s44, 0x40000
	v_lshl_add_u64 v[202:203], s[44:45], 0, v[130:131]
	s_addc_u32 s71, s45, 0
	s_add_i32 s69, s62, s16
	global_load_lds_dwordx4 v[202:203], off
	v_lshl_add_u64 v[222:223], s[70:71], 0, v[134:135]
	s_mov_b32 m0, s69
	v_lshl_add_u64 v[224:225], s[46:47], 0, v[132:133]
	global_load_lds_dwordx4 v[222:223], off
	v_lshl_add_u64 v[222:223], s[70:71], 0, v[130:131]
	s_add_i32 m0, s69, 0x2000
	s_nop 0
	global_load_lds_dwordx4 v[222:223], off
	v_lshl_add_u64 v[222:223], s[46:47], 0, v[136:137]
	s_mov_b32 m0, s19
	s_nop 0
	global_load_lds_dwordx4 v[222:223], off
	s_mov_b32 m0, s24
	s_nop 0
	global_load_lds_dwordx4 v[224:225], off
	s_waitcnt vmcnt(8)
	s_waitcnt lgkmcnt(0)
	s_barrier
	s_setprio 1
	s_waitcnt lgkmcnt(0)
	v_mfma_f32_16x16x32_bf16 v[62:65], v[154:157], v[186:189], 0
	v_mfma_f32_16x16x32_bf16 v[58:61], v[162:165], v[186:189], 0
	v_mfma_f32_16x16x32_bf16 v[46:49], v[154:157], v[194:197], 0
	v_mfma_f32_16x16x32_bf16 v[42:45], v[162:165], v[194:197], 0
	v_mfma_f32_16x16x32_bf16 v[30:33], v[154:157], v[206:209], 0
	v_mfma_f32_16x16x32_bf16 v[26:29], v[162:165], v[206:209], 0
	v_mfma_f32_16x16x32_bf16 v[14:17], v[154:157], v[214:217], 0
	v_mfma_f32_16x16x32_bf16 v[10:13], v[162:165], v[214:217], 0
	v_mfma_f32_16x16x32_bf16 v[62:65], v[158:161], v[190:193], v[62:65]
	v_mfma_f32_16x16x32_bf16 v[58:61], v[166:169], v[190:193], v[58:61]
	v_mfma_f32_16x16x32_bf16 v[46:49], v[158:161], v[198:201], v[46:49]
	v_mfma_f32_16x16x32_bf16 v[42:45], v[166:169], v[198:201], v[42:45]
	v_mfma_f32_16x16x32_bf16 v[30:33], v[158:161], v[210:213], v[30:33]
	v_mfma_f32_16x16x32_bf16 v[26:29], v[166:169], v[210:213], v[26:29]
	v_mfma_f32_16x16x32_bf16 v[14:17], v[158:161], v[218:221], v[14:17]
	v_mfma_f32_16x16x32_bf16 v[10:13], v[166:169], v[218:221], v[10:13]
	s_setprio 0
	s_setprio 1
	v_mfma_f32_16x16x32_bf16 v[54:57], v[170:173], v[186:189], 0
	v_mfma_f32_16x16x32_bf16 v[50:53], v[178:181], v[186:189], 0
	v_mfma_f32_16x16x32_bf16 v[38:41], v[170:173], v[194:197], 0
	v_mfma_f32_16x16x32_bf16 v[34:37], v[178:181], v[194:197], 0
	v_mfma_f32_16x16x32_bf16 v[22:25], v[170:173], v[206:209], 0
	v_mfma_f32_16x16x32_bf16 v[18:21], v[178:181], v[206:209], 0
	v_mfma_f32_16x16x32_bf16 v[6:9], v[170:173], v[214:217], 0
	v_mfma_f32_16x16x32_bf16 v[2:5], v[178:181], v[214:217], 0
	v_mfma_f32_16x16x32_bf16 v[54:57], v[174:177], v[190:193], v[54:57]
	v_mfma_f32_16x16x32_bf16 v[50:53], v[182:185], v[190:193], v[50:53]
	v_mfma_f32_16x16x32_bf16 v[38:41], v[174:177], v[198:201], v[38:41]
	v_mfma_f32_16x16x32_bf16 v[34:37], v[182:185], v[198:201], v[34:37]
	v_mfma_f32_16x16x32_bf16 v[22:25], v[174:177], v[210:213], v[22:25]
	v_mfma_f32_16x16x32_bf16 v[18:21], v[182:185], v[210:213], v[18:21]
	v_mfma_f32_16x16x32_bf16 v[6:9], v[174:177], v[218:221], v[6:9]
	v_mfma_f32_16x16x32_bf16 v[2:5], v[182:185], v[218:221], v[2:5]
	s_setprio 0
	s_barrier
	s_add_i32 s69, 0, 0x18000
	v_add_u32_e32 v153, s69, v149
	s_add_i32 s70, 0, 0x1c000
	ds_read_b128 v[154:157], v153
	ds_read_b128 v[158:161], v153 offset:1024
	ds_read_b128 v[162:165], v153 offset:2048
	ds_read_b128 v[166:169], v153 offset:3072
	v_add_u32_e32 v153, s70, v149
	ds_read_b128 v[170:173], v153
	ds_read_b128 v[174:177], v153 offset:1024
	ds_read_b128 v[178:181], v153 offset:2048
	ds_read_b128 v[182:185], v153 offset:3072
	s_add_u32 s46, s46, 0x40000
	s_addc_u32 s47, s47, 0
	s_mov_b32 m0, s25
	v_lshl_add_u64 v[226:227], s[46:47], 0, v[136:137]
	ds_read_b128 v[186:189], v152 offset:32768
	ds_read_b128 v[190:193], v152 offset:33792
	ds_read_b128 v[194:197], v152 offset:34816
	ds_read_b128 v[198:201], v152 offset:35840
	ds_read_b128 v[206:209], v152 offset:36864
	ds_read_b128 v[210:213], v152 offset:37888
	ds_read_b128 v[214:217], v152 offset:38912
	ds_read_b128 v[218:221], v152 offset:39936
	global_load_lds_dwordx4 v[226:227], off
	v_lshl_add_u64 v[226:227], s[46:47], 0, v[132:133]
	s_mov_b32 m0, s28
	s_nop 0
	global_load_lds_dwordx4 v[226:227], off
	s_waitcnt vmcnt(8)
	s_waitcnt lgkmcnt(0)
	s_barrier
	s_setprio 1
	s_waitcnt lgkmcnt(0)
	v_mfma_f32_16x16x32_bf16 v[126:129], v[154:157], v[186:189], v[126:129]
	v_mfma_f32_16x16x32_bf16 v[122:125], v[162:165], v[186:189], v[122:125]
	v_mfma_f32_16x16x32_bf16 v[110:113], v[154:157], v[194:197], v[110:113]
	v_mfma_f32_16x16x32_bf16 v[106:109], v[162:165], v[194:197], v[106:109]
	v_mfma_f32_16x16x32_bf16 v[94:97], v[154:157], v[206:209], v[94:97]
	v_mfma_f32_16x16x32_bf16 v[90:93], v[162:165], v[206:209], v[90:93]
	v_mfma_f32_16x16x32_bf16 v[78:81], v[154:157], v[214:217], v[78:81]
	v_mfma_f32_16x16x32_bf16 v[74:77], v[162:165], v[214:217], v[74:77]
	v_mfma_f32_16x16x32_bf16 v[126:129], v[158:161], v[190:193], v[126:129]
	v_mfma_f32_16x16x32_bf16 v[122:125], v[166:169], v[190:193], v[122:125]
	v_mfma_f32_16x16x32_bf16 v[110:113], v[158:161], v[198:201], v[110:113]
	v_mfma_f32_16x16x32_bf16 v[106:109], v[166:169], v[198:201], v[106:109]
	v_mfma_f32_16x16x32_bf16 v[94:97], v[158:161], v[210:213], v[94:97]
	v_mfma_f32_16x16x32_bf16 v[90:93], v[166:169], v[210:213], v[90:93]
	v_mfma_f32_16x16x32_bf16 v[78:81], v[158:161], v[218:221], v[78:81]
	v_mfma_f32_16x16x32_bf16 v[74:77], v[166:169], v[218:221], v[74:77]
	s_setprio 0
	s_setprio 1
	v_mfma_f32_16x16x32_bf16 v[118:121], v[170:173], v[186:189], v[118:121]
	v_mfma_f32_16x16x32_bf16 v[114:117], v[178:181], v[186:189], v[114:117]
	v_mfma_f32_16x16x32_bf16 v[102:105], v[170:173], v[194:197], v[102:105]
	v_mfma_f32_16x16x32_bf16 v[98:101], v[178:181], v[194:197], v[98:101]
	v_mfma_f32_16x16x32_bf16 v[86:89], v[170:173], v[206:209], v[86:89]
	v_mfma_f32_16x16x32_bf16 v[82:85], v[178:181], v[206:209], v[82:85]
	v_mfma_f32_16x16x32_bf16 v[70:73], v[170:173], v[214:217], v[70:73]
	v_mfma_f32_16x16x32_bf16 v[66:69], v[178:181], v[214:217], v[66:69]
	v_mfma_f32_16x16x32_bf16 v[118:121], v[174:177], v[190:193], v[118:121]
	v_mfma_f32_16x16x32_bf16 v[114:117], v[182:185], v[190:193], v[114:117]
	v_mfma_f32_16x16x32_bf16 v[102:105], v[174:177], v[198:201], v[102:105]
	v_mfma_f32_16x16x32_bf16 v[98:101], v[182:185], v[198:201], v[98:101]
	v_mfma_f32_16x16x32_bf16 v[86:89], v[174:177], v[210:213], v[86:89]
	v_mfma_f32_16x16x32_bf16 v[82:85], v[182:185], v[210:213], v[82:85]
	v_mfma_f32_16x16x32_bf16 v[70:73], v[174:177], v[218:221], v[70:73]
	v_mfma_f32_16x16x32_bf16 v[66:69], v[182:185], v[218:221], v[66:69]
	s_setprio 0
	s_barrier
	s_add_i32 s46, s69, s16
	v_lshl_add_u64 v[146:147], v[146:147], 0, s[10:11]
	s_mov_b32 m0, s46
	ds_read_b128 v[186:189], v152 offset:49152
	ds_read_b128 v[190:193], v152 offset:50176
	ds_read_b128 v[194:197], v152 offset:51200
	ds_read_b128 v[198:201], v152 offset:52224
	ds_read_b128 v[206:209], v152 offset:53248
	ds_read_b128 v[210:213], v152 offset:54272
	ds_read_b128 v[214:217], v152 offset:55296
	ds_read_b128 v[218:221], v152 offset:56320
	global_load_lds_dwordx4 v[146:147], off
	s_add_i32 m0, s46, 0x2000
	s_add_u32 s44, s44, 0x40080
	v_lshl_add_u64 v[146:147], v[202:203], 0, s[10:11]
	s_addc_u32 s45, s45, 0
	s_add_i32 s46, s70, s16
	global_load_lds_dwordx4 v[146:147], off
	v_lshl_add_u64 v[146:147], s[44:45], 0, v[134:135]
	s_mov_b32 m0, s46
	s_nop 0
	global_load_lds_dwordx4 v[146:147], off
	v_lshl_add_u64 v[146:147], s[44:45], 0, v[130:131]
	s_add_i32 m0, s46, 0x2000
	s_nop 0
	global_load_lds_dwordx4 v[146:147], off
	v_lshl_add_u64 v[146:147], v[222:223], 0, s[10:11]
	s_mov_b32 m0, s33
	s_nop 0
	global_load_lds_dwordx4 v[146:147], off
	v_lshl_add_u64 v[146:147], v[224:225], 0, s[10:11]
	s_mov_b32 m0, s35
	s_nop 0
	global_load_lds_dwordx4 v[146:147], off
	s_waitcnt vmcnt(8)
	s_waitcnt lgkmcnt(0)
	s_barrier
	s_setprio 1
	s_waitcnt lgkmcnt(0)
	v_mfma_f32_16x16x32_bf16 v[62:65], v[154:157], v[186:189], v[62:65]
	v_mfma_f32_16x16x32_bf16 v[58:61], v[162:165], v[186:189], v[58:61]
	v_mfma_f32_16x16x32_bf16 v[46:49], v[154:157], v[194:197], v[46:49]
	v_mfma_f32_16x16x32_bf16 v[42:45], v[162:165], v[194:197], v[42:45]
	v_mfma_f32_16x16x32_bf16 v[30:33], v[154:157], v[206:209], v[30:33]
	v_mfma_f32_16x16x32_bf16 v[26:29], v[162:165], v[206:209], v[26:29]
	v_mfma_f32_16x16x32_bf16 v[14:17], v[154:157], v[214:217], v[14:17]
	v_mfma_f32_16x16x32_bf16 v[10:13], v[162:165], v[214:217], v[10:13]
	v_mfma_f32_16x16x32_bf16 v[62:65], v[158:161], v[190:193], v[62:65]
	v_mfma_f32_16x16x32_bf16 v[58:61], v[166:169], v[190:193], v[58:61]
	v_mfma_f32_16x16x32_bf16 v[46:49], v[158:161], v[198:201], v[46:49]
	v_mfma_f32_16x16x32_bf16 v[42:45], v[166:169], v[198:201], v[42:45]
	v_mfma_f32_16x16x32_bf16 v[30:33], v[158:161], v[210:213], v[30:33]
	v_mfma_f32_16x16x32_bf16 v[26:29], v[166:169], v[210:213], v[26:29]
	v_mfma_f32_16x16x32_bf16 v[14:17], v[158:161], v[218:221], v[14:17]
	v_mfma_f32_16x16x32_bf16 v[10:13], v[166:169], v[218:221], v[10:13]
	s_setprio 0
	s_setprio 1
	v_mfma_f32_16x16x32_bf16 v[54:57], v[170:173], v[186:189], v[54:57]
	v_mfma_f32_16x16x32_bf16 v[50:53], v[178:181], v[186:189], v[50:53]
	v_mfma_f32_16x16x32_bf16 v[38:41], v[170:173], v[194:197], v[38:41]
	v_mfma_f32_16x16x32_bf16 v[34:37], v[178:181], v[194:197], v[34:37]
	v_mfma_f32_16x16x32_bf16 v[22:25], v[170:173], v[206:209], v[22:25]
	v_mfma_f32_16x16x32_bf16 v[18:21], v[178:181], v[206:209], v[18:21]
	v_mfma_f32_16x16x32_bf16 v[6:9], v[170:173], v[214:217], v[6:9]
	v_mfma_f32_16x16x32_bf16 v[2:5], v[178:181], v[214:217], v[2:5]
	v_mfma_f32_16x16x32_bf16 v[54:57], v[174:177], v[190:193], v[54:57]
	v_mfma_f32_16x16x32_bf16 v[50:53], v[182:185], v[190:193], v[50:53]
	v_mfma_f32_16x16x32_bf16 v[38:41], v[174:177], v[198:201], v[38:41]
	v_mfma_f32_16x16x32_bf16 v[34:37], v[182:185], v[198:201], v[34:37]
	v_mfma_f32_16x16x32_bf16 v[22:25], v[174:177], v[210:213], v[22:25]
	v_mfma_f32_16x16x32_bf16 v[18:21], v[182:185], v[210:213], v[18:21]
	v_mfma_f32_16x16x32_bf16 v[6:9], v[174:177], v[218:221], v[6:9]
	v_mfma_f32_16x16x32_bf16 v[2:5], v[182:185], v[218:221], v[2:5]
	s_setprio 0
	s_barrier
	s_add_i32 s68, s68, 2
	s_add_u32 s42, s42, 0x100
	s_addc_u32 s43, s43, 0
	s_add_u32 s66, s66, 0x100
	s_addc_u32 s67, s67, 0
	s_cmp_gt_u32 s68, 13

.LBB0_833:
	s_add_u32 s72, s0, s68
	s_addc_u32 s73, s1, s69
	s_and_b64 s[62:63], s[70:71], exec
	s_cselect_b32 s15, s73, s77
	s_cselect_b32 s33, s72, s76
	s_add_u32 s74, s35, s66
	s_addc_u32 s75, s85, s67
	s_and_b64 s[62:63], s[70:71], exec
	s_cselect_b32 s34, s75, s79
	s_cselect_b32 s39, s74, s78
	s_add_i32 s45, s7, -2
	s_add_u32 s76, s76, 0x100080
	s_addc_u32 s77, s77, 0
	s_add_u32 s47, s78, 0x100
	s_addc_u32 s62, s79, 0
	s_mov_b32 s63, 0
	s_waitcnt vmcnt(0)
	ds_read_b128 v[114:117], v190
	ds_read_b128 v[118:121], v190 offset:1024
	ds_read_b128 v[122:125], v190 offset:2048
	ds_read_b128 v[126:129], v190 offset:3072
	ds_read_b128 v[146:149], v191
	ds_read_b128 v[150:153], v191 offset:1024
	ds_read_b128 v[154:157], v191 offset:2048
	ds_read_b128 v[158:161], v191 offset:3072
	s_add_i32 s82, s63, 2
	s_add_u32 s78, s76, 0xfff00080
	s_addc_u32 s79, s77, -1
	s_cmp_eq_u32 s45, s63
	s_cselect_b32 s81, s15, s79
	s_cselect_b32 s80, s33, s78
	s_cselect_b32 s79, s34, s62
	s_cselect_b32 s78, s39, s47
	v_lshl_add_u64 v[186:187], s[76:77], 0, v[180:181]
	s_add_i32 m0, s87, 0xc000
	ds_read_b128 v[162:165], v192
	ds_read_b128 v[166:169], v192 offset:1024
	ds_read_b128 v[194:197], v192 offset:2048
	ds_read_b128 v[198:201], v192 offset:3072
	ds_read_b128 v[206:209], v192 offset:4096
	ds_read_b128 v[210:213], v192 offset:5120
	ds_read_b128 v[214:217], v192 offset:6144
	ds_read_b128 v[218:221], v192 offset:7168
	global_load_lds_dwordx4 v[186:187], off
	v_lshl_add_u64 v[186:187], s[76:77], 0, v[182:183]
	s_add_i32 m0, s87, 0xe000
	s_nop 0
	global_load_lds_dwordx4 v[186:187], off
	s_waitcnt vmcnt(8)
	s_waitcnt lgkmcnt(0)
	s_barrier
	s_setprio 1
	s_waitcnt lgkmcnt(0)
	v_mfma_f32_16x16x32_bf16 v[142:145], v[114:117], v[162:165], 0
	v_mfma_f32_16x16x32_bf16 v[138:141], v[122:125], v[162:165], 0
	v_mfma_f32_16x16x32_bf16 v[110:113], v[114:117], v[194:197], 0
	v_mfma_f32_16x16x32_bf16 v[106:109], v[122:125], v[194:197], 0
	v_mfma_f32_16x16x32_bf16 v[98:101], v[114:117], v[206:209], 0
	v_mfma_f32_16x16x32_bf16 v[90:93], v[122:125], v[206:209], 0
	v_mfma_f32_16x16x32_bf16 v[82:85], v[114:117], v[214:217], 0
	v_mfma_f32_16x16x32_bf16 v[74:77], v[122:125], v[214:217], 0
	v_mfma_f32_16x16x32_bf16 v[142:145], v[118:121], v[166:169], v[142:145]
	v_mfma_f32_16x16x32_bf16 v[138:141], v[126:129], v[166:169], v[138:141]
	v_mfma_f32_16x16x32_bf16 v[110:113], v[118:121], v[198:201], v[110:113]
	v_mfma_f32_16x16x32_bf16 v[106:109], v[126:129], v[198:201], v[106:109]
	v_mfma_f32_16x16x32_bf16 v[98:101], v[118:121], v[210:213], v[98:101]
	v_mfma_f32_16x16x32_bf16 v[90:93], v[126:129], v[210:213], v[90:93]
	v_mfma_f32_16x16x32_bf16 v[82:85], v[118:121], v[218:221], v[82:85]
	v_mfma_f32_16x16x32_bf16 v[74:77], v[126:129], v[218:221], v[74:77]
	s_setprio 0
	s_setprio 1
	v_mfma_f32_16x16x32_bf16 v[134:137], v[146:149], v[162:165], 0
	v_mfma_f32_16x16x32_bf16 v[130:133], v[154:157], v[162:165], 0
	v_mfma_f32_16x16x32_bf16 v[102:105], v[146:149], v[194:197], 0
	v_mfma_f32_16x16x32_bf16 v[94:97], v[154:157], v[194:197], 0
	v_mfma_f32_16x16x32_bf16 v[86:89], v[146:149], v[206:209], 0
	v_mfma_f32_16x16x32_bf16 v[78:81], v[154:157], v[206:209], 0
	v_mfma_f32_16x16x32_bf16 v[70:73], v[146:149], v[214:217], 0
	v_mfma_f32_16x16x32_bf16 v[66:69], v[154:157], v[214:217], 0
	v_mfma_f32_16x16x32_bf16 v[134:137], v[150:153], v[166:169], v[134:137]
	v_mfma_f32_16x16x32_bf16 v[130:133], v[158:161], v[166:169], v[130:133]
	v_mfma_f32_16x16x32_bf16 v[102:105], v[150:153], v[198:201], v[102:105]
	v_mfma_f32_16x16x32_bf16 v[94:97], v[158:161], v[198:201], v[94:97]
	v_mfma_f32_16x16x32_bf16 v[86:89], v[150:153], v[210:213], v[86:89]
	v_mfma_f32_16x16x32_bf16 v[78:81], v[158:161], v[210:213], v[78:81]
	v_mfma_f32_16x16x32_bf16 v[70:73], v[150:153], v[218:221], v[70:73]
	v_mfma_f32_16x16x32_bf16 v[66:69], v[158:161], v[218:221], v[66:69]
	s_setprio 0
	s_barrier
	s_add_i32 s63, s24, s86
	v_lshl_add_u64 v[186:187], s[78:79], 0, v[172:173]
	s_mov_b32 m0, s63
	ds_read_b128 v[162:165], v192 offset:16384
	ds_read_b128 v[166:169], v192 offset:17408
	ds_read_b128 v[194:197], v192 offset:18432
	ds_read_b128 v[198:201], v192 offset:19456
	ds_read_b128 v[206:209], v192 offset:20480
	ds_read_b128 v[210:213], v192 offset:21504
	ds_read_b128 v[214:217], v192 offset:22528
	ds_read_b128 v[218:221], v192 offset:23552
	global_load_lds_dwordx4 v[186:187], off
	s_add_i32 m0, s63, 0x2000
	s_add_u32 vcc_lo, s78, 0x100000
	v_lshl_add_u64 v[202:203], s[78:79], 0, v[176:177]
	s_addc_u32 vcc_hi, s79, 0
	s_add_i32 s63, s25, s86
	global_load_lds_dwordx4 v[202:203], off
	v_lshl_add_u64 v[222:223], vcc, 0, v[172:173]
	s_mov_b32 m0, s63
	v_lshl_add_u64 v[224:225], s[80:81], 0, v[174:175]
	global_load_lds_dwordx4 v[222:223], off
	v_lshl_add_u64 v[222:223], vcc, 0, v[176:177]
	s_add_i32 m0, s63, 0x2000
	s_nop 0
	global_load_lds_dwordx4 v[222:223], off
	v_lshl_add_u64 v[222:223], s[80:81], 0, v[170:171]
	s_mov_b32 m0, s87
	s_nop 0
	global_load_lds_dwordx4 v[222:223], off
	s_mov_b32 m0, s88
	s_nop 0
	global_load_lds_dwordx4 v[224:225], off
	s_waitcnt vmcnt(8)
	s_waitcnt lgkmcnt(0)
	s_barrier
	s_setprio 1
	s_waitcnt lgkmcnt(0)
	v_mfma_f32_16x16x32_bf16 v[62:65], v[114:117], v[162:165], 0
	v_mfma_f32_16x16x32_bf16 v[58:61], v[122:125], v[162:165], 0
	v_mfma_f32_16x16x32_bf16 v[50:53], v[114:117], v[194:197], 0
	v_mfma_f32_16x16x32_bf16 v[42:45], v[122:125], v[194:197], 0
	v_mfma_f32_16x16x32_bf16 v[34:37], v[114:117], v[206:209], 0
	v_mfma_f32_16x16x32_bf16 v[26:29], v[122:125], v[206:209], 0
	v_mfma_f32_16x16x32_bf16 v[18:21], v[114:117], v[214:217], 0
	v_mfma_f32_16x16x32_bf16 v[10:13], v[122:125], v[214:217], 0
	v_mfma_f32_16x16x32_bf16 v[62:65], v[118:121], v[166:169], v[62:65]
	v_mfma_f32_16x16x32_bf16 v[58:61], v[126:129], v[166:169], v[58:61]
	v_mfma_f32_16x16x32_bf16 v[50:53], v[118:121], v[198:201], v[50:53]
	v_mfma_f32_16x16x32_bf16 v[42:45], v[126:129], v[198:201], v[42:45]
	v_mfma_f32_16x16x32_bf16 v[34:37], v[118:121], v[210:213], v[34:37]
	v_mfma_f32_16x16x32_bf16 v[26:29], v[126:129], v[210:213], v[26:29]
	v_mfma_f32_16x16x32_bf16 v[18:21], v[118:121], v[218:221], v[18:21]
	v_mfma_f32_16x16x32_bf16 v[10:13], v[126:129], v[218:221], v[10:13]
	s_setprio 0
	s_setprio 1
	v_mfma_f32_16x16x32_bf16 v[54:57], v[146:149], v[162:165], 0
	v_mfma_f32_16x16x32_bf16 v[46:49], v[154:157], v[162:165], 0
	v_mfma_f32_16x16x32_bf16 v[38:41], v[146:149], v[194:197], 0
	v_mfma_f32_16x16x32_bf16 v[30:33], v[154:157], v[194:197], 0
	v_mfma_f32_16x16x32_bf16 v[22:25], v[146:149], v[206:209], 0
	v_mfma_f32_16x16x32_bf16 v[14:17], v[154:157], v[206:209], 0
	v_mfma_f32_16x16x32_bf16 v[6:9], v[146:149], v[214:217], 0
	v_mfma_f32_16x16x32_bf16 v[2:5], v[154:157], v[214:217], 0
	v_mfma_f32_16x16x32_bf16 v[54:57], v[150:153], v[166:169], v[54:57]
	v_mfma_f32_16x16x32_bf16 v[46:49], v[158:161], v[166:169], v[46:49]
	v_mfma_f32_16x16x32_bf16 v[38:41], v[150:153], v[198:201], v[38:41]
	v_mfma_f32_16x16x32_bf16 v[30:33], v[158:161], v[198:201], v[30:33]
	v_mfma_f32_16x16x32_bf16 v[22:25], v[150:153], v[210:213], v[22:25]
	v_mfma_f32_16x16x32_bf16 v[14:17], v[158:161], v[210:213], v[14:17]
	v_mfma_f32_16x16x32_bf16 v[6:9], v[150:153], v[218:221], v[6:9]
	v_mfma_f32_16x16x32_bf16 v[2:5], v[158:161], v[218:221], v[2:5]
	s_setprio 0
	s_barrier
	s_add_i32 s63, 0, 0x18000
	s_add_i32 s83, 0, 0x1c000
	v_add_u32_e32 v126, s63, v189
	v_add_u32_e32 v158, s83, v189
	ds_read_b128 v[114:117], v126
	ds_read_b128 v[118:121], v126 offset:1024
	ds_read_b128 v[122:125], v126 offset:2048
	ds_read_b128 v[126:129], v126 offset:3072
	ds_read_b128 v[146:149], v158
	ds_read_b128 v[150:153], v158 offset:1024
	ds_read_b128 v[154:157], v158 offset:2048
	ds_read_b128 v[158:161], v158 offset:3072
	s_add_u32 s80, s80, 0x100000
	s_addc_u32 s81, s81, 0
	s_mov_b32 m0, s89
	v_lshl_add_u64 v[226:227], s[80:81], 0, v[170:171]
	ds_read_b128 v[162:165], v192 offset:32768
	ds_read_b128 v[166:169], v192 offset:33792
	ds_read_b128 v[194:197], v192 offset:34816
	ds_read_b128 v[198:201], v192 offset:35840
	ds_read_b128 v[206:209], v192 offset:36864
	ds_read_b128 v[210:213], v192 offset:37888
	ds_read_b128 v[214:217], v192 offset:38912
	ds_read_b128 v[218:221], v192 offset:39936
	global_load_lds_dwordx4 v[226:227], off
	v_lshl_add_u64 v[226:227], s[80:81], 0, v[174:175]
	s_mov_b32 m0, s90
	s_nop 0
	global_load_lds_dwordx4 v[226:227], off
	s_waitcnt vmcnt(8)
	s_waitcnt lgkmcnt(0)
	s_barrier
	s_setprio 1
	s_waitcnt lgkmcnt(0)
	v_mfma_f32_16x16x32_bf16 v[142:145], v[114:117], v[162:165], v[142:145]
	v_mfma_f32_16x16x32_bf16 v[138:141], v[122:125], v[162:165], v[138:141]
	v_mfma_f32_16x16x32_bf16 v[110:113], v[114:117], v[194:197], v[110:113]
	v_mfma_f32_16x16x32_bf16 v[106:109], v[122:125], v[194:197], v[106:109]
	v_mfma_f32_16x16x32_bf16 v[98:101], v[114:117], v[206:209], v[98:101]
	v_mfma_f32_16x16x32_bf16 v[90:93], v[122:125], v[206:209], v[90:93]
	v_mfma_f32_16x16x32_bf16 v[82:85], v[114:117], v[214:217], v[82:85]
	v_mfma_f32_16x16x32_bf16 v[74:77], v[122:125], v[214:217], v[74:77]
	v_mfma_f32_16x16x32_bf16 v[142:145], v[118:121], v[166:169], v[142:145]
	v_mfma_f32_16x16x32_bf16 v[138:141], v[126:129], v[166:169], v[138:141]
	v_mfma_f32_16x16x32_bf16 v[110:113], v[118:121], v[198:201], v[110:113]
	v_mfma_f32_16x16x32_bf16 v[106:109], v[126:129], v[198:201], v[106:109]
	v_mfma_f32_16x16x32_bf16 v[98:101], v[118:121], v[210:213], v[98:101]
	v_mfma_f32_16x16x32_bf16 v[90:93], v[126:129], v[210:213], v[90:93]
	v_mfma_f32_16x16x32_bf16 v[82:85], v[118:121], v[218:221], v[82:85]
	v_mfma_f32_16x16x32_bf16 v[74:77], v[126:129], v[218:221], v[74:77]
	s_setprio 0
	s_setprio 1
	v_mfma_f32_16x16x32_bf16 v[134:137], v[146:149], v[162:165], v[134:137]
	v_mfma_f32_16x16x32_bf16 v[130:133], v[154:157], v[162:165], v[130:133]
	v_mfma_f32_16x16x32_bf16 v[102:105], v[146:149], v[194:197], v[102:105]
	v_mfma_f32_16x16x32_bf16 v[94:97], v[154:157], v[194:197], v[94:97]
	v_mfma_f32_16x16x32_bf16 v[86:89], v[146:149], v[206:209], v[86:89]
	v_mfma_f32_16x16x32_bf16 v[78:81], v[154:157], v[206:209], v[78:81]
	v_mfma_f32_16x16x32_bf16 v[70:73], v[146:149], v[214:217], v[70:73]
	v_mfma_f32_16x16x32_bf16 v[66:69], v[154:157], v[214:217], v[66:69]
	v_mfma_f32_16x16x32_bf16 v[134:137], v[150:153], v[166:169], v[134:137]
	v_mfma_f32_16x16x32_bf16 v[130:133], v[158:161], v[166:169], v[130:133]
	v_mfma_f32_16x16x32_bf16 v[102:105], v[150:153], v[198:201], v[102:105]
	v_mfma_f32_16x16x32_bf16 v[94:97], v[158:161], v[198:201], v[94:97]
	v_mfma_f32_16x16x32_bf16 v[86:89], v[150:153], v[210:213], v[86:89]
	v_mfma_f32_16x16x32_bf16 v[78:81], v[158:161], v[210:213], v[78:81]
	v_mfma_f32_16x16x32_bf16 v[70:73], v[150:153], v[218:221], v[70:73]
	v_mfma_f32_16x16x32_bf16 v[66:69], v[158:161], v[218:221], v[66:69]
	s_setprio 0
	s_barrier
	s_add_i32 s63, s63, s86
	v_lshl_add_u64 v[186:187], v[186:187], 0, s[22:23]
	s_mov_b32 m0, s63
	ds_read_b128 v[162:165], v192 offset:49152
	ds_read_b128 v[166:169], v192 offset:50176
	ds_read_b128 v[194:197], v192 offset:51200
	ds_read_b128 v[198:201], v192 offset:52224
	ds_read_b128 v[206:209], v192 offset:53248
	ds_read_b128 v[210:213], v192 offset:54272
	ds_read_b128 v[214:217], v192 offset:55296
	ds_read_b128 v[218:221], v192 offset:56320
	global_load_lds_dwordx4 v[186:187], off
	s_add_i32 m0, s63, 0x2000
	s_add_u32 s78, s78, 0x100080
	v_lshl_add_u64 v[186:187], v[202:203], 0, s[22:23]
	s_addc_u32 s79, s79, 0
	s_add_i32 s63, s83, s86
	global_load_lds_dwordx4 v[186:187], off
	v_lshl_add_u64 v[186:187], s[78:79], 0, v[172:173]
	s_mov_b32 m0, s63
	s_nop 0
	global_load_lds_dwordx4 v[186:187], off
	v_lshl_add_u64 v[186:187], s[78:79], 0, v[176:177]
	s_add_i32 m0, s63, 0x2000
	s_nop 0
	global_load_lds_dwordx4 v[186:187], off
	v_lshl_add_u64 v[186:187], v[222:223], 0, s[22:23]
	s_mov_b32 m0, s95
	s_nop 0
	global_load_lds_dwordx4 v[186:187], off
	v_lshl_add_u64 v[186:187], v[224:225], 0, s[22:23]
	s_mov_b32 m0, s96
	s_nop 0
	global_load_lds_dwordx4 v[186:187], off
	s_waitcnt vmcnt(8)
	s_waitcnt lgkmcnt(0)
	s_barrier
	s_setprio 1
	s_waitcnt lgkmcnt(0)
	v_mfma_f32_16x16x32_bf16 v[62:65], v[114:117], v[162:165], v[62:65]
	v_mfma_f32_16x16x32_bf16 v[58:61], v[122:125], v[162:165], v[58:61]
	v_mfma_f32_16x16x32_bf16 v[50:53], v[114:117], v[194:197], v[50:53]
	v_mfma_f32_16x16x32_bf16 v[42:45], v[122:125], v[194:197], v[42:45]
	v_mfma_f32_16x16x32_bf16 v[34:37], v[114:117], v[206:209], v[34:37]
	v_mfma_f32_16x16x32_bf16 v[26:29], v[122:125], v[206:209], v[26:29]
	v_mfma_f32_16x16x32_bf16 v[18:21], v[114:117], v[214:217], v[18:21]
	v_mfma_f32_16x16x32_bf16 v[10:13], v[122:125], v[214:217], v[10:13]
	v_mfma_f32_16x16x32_bf16 v[62:65], v[118:121], v[166:169], v[62:65]
	v_mfma_f32_16x16x32_bf16 v[58:61], v[126:129], v[166:169], v[58:61]
	v_mfma_f32_16x16x32_bf16 v[50:53], v[118:121], v[198:201], v[50:53]
	v_mfma_f32_16x16x32_bf16 v[42:45], v[126:129], v[198:201], v[42:45]
	v_mfma_f32_16x16x32_bf16 v[34:37], v[118:121], v[210:213], v[34:37]
	v_mfma_f32_16x16x32_bf16 v[26:29], v[126:129], v[210:213], v[26:29]
	v_mfma_f32_16x16x32_bf16 v[18:21], v[118:121], v[218:221], v[18:21]
	v_mfma_f32_16x16x32_bf16 v[10:13], v[126:129], v[218:221], v[10:13]
	s_setprio 0
	s_setprio 1
	v_mfma_f32_16x16x32_bf16 v[54:57], v[146:149], v[162:165], v[54:57]
	v_mfma_f32_16x16x32_bf16 v[46:49], v[154:157], v[162:165], v[46:49]
	v_mfma_f32_16x16x32_bf16 v[38:41], v[146:149], v[194:197], v[38:41]
	v_mfma_f32_16x16x32_bf16 v[30:33], v[154:157], v[194:197], v[30:33]
	v_mfma_f32_16x16x32_bf16 v[22:25], v[146:149], v[206:209], v[22:25]
	v_mfma_f32_16x16x32_bf16 v[14:17], v[154:157], v[206:209], v[14:17]
	v_mfma_f32_16x16x32_bf16 v[6:9], v[146:149], v[214:217], v[6:9]
	v_mfma_f32_16x16x32_bf16 v[2:5], v[154:157], v[214:217], v[2:5]
	v_mfma_f32_16x16x32_bf16 v[54:57], v[150:153], v[166:169], v[54:57]
	v_mfma_f32_16x16x32_bf16 v[46:49], v[158:161], v[166:169], v[46:49]
	v_mfma_f32_16x16x32_bf16 v[38:41], v[150:153], v[198:201], v[38:41]
	v_mfma_f32_16x16x32_bf16 v[30:33], v[158:161], v[198:201], v[30:33]
	v_mfma_f32_16x16x32_bf16 v[22:25], v[150:153], v[210:213], v[22:25]
	v_mfma_f32_16x16x32_bf16 v[14:17], v[158:161], v[210:213], v[14:17]
	v_mfma_f32_16x16x32_bf16 v[6:9], v[150:153], v[218:221], v[6:9]
	v_mfma_f32_16x16x32_bf16 v[2:5], v[158:161], v[218:221], v[2:5]
	s_setprio 0
	s_barrier
	s_add_u32 s76, s76, 0x100
	s_addc_u32 s77, s77, 0
	s_add_u32 s47, s47, 0x100
	s_addc_u32 s62, s62, 0
	s_cmp_ge_i32 s82, s7
	s_mov_b32 s63, s82

.LBB0_1012:
	s_add_u32 s48, s96, s44
	s_addc_u32 s49, s97, s45
	s_and_b64 s[14:15], s[4:5], exec
	s_cselect_b32 s6, s49, s65
	s_cselect_b32 s14, s48, s64
	s_add_u32 s50, s3, s46
	s_addc_u32 s51, s35, s47
	s_and_b64 s[18:19], s[4:5], exec
	s_cselect_b32 s15, s51, s67
	s_cselect_b32 s17, s50, s66
	s_add_u32 s64, s64, 0x40080
	s_addc_u32 s65, s65, 0
	s_add_u32 s18, s66, 0x100
	s_addc_u32 s19, s67, 0
	s_mov_b32 s24, -2
	s_waitcnt vmcnt(0)
	ds_read_b128 v[130:133], v172
	ds_read_b128 v[134:137], v172 offset:1024
	ds_read_b128 v[138:141], v172 offset:2048
	ds_read_b128 v[142:145], v172 offset:3072
	ds_read_b128 v[164:167], v173
	ds_read_b128 v[176:179], v173 offset:1024
	ds_read_b128 v[180:183], v173 offset:2048
	ds_read_b128 v[184:187], v173 offset:3072
	s_add_u32 s25, s64, 0xfffc0080
	s_addc_u32 s28, s65, -1
	s_cmp_eq_u32 s24, 12
	s_cselect_b32 s69, s6, s28
	s_cselect_b32 s68, s14, s25
	s_cselect_b32 s67, s15, s19
	s_cselect_b32 s66, s17, s18
	v_lshl_add_u64 v[168:169], s[64:65], 0, v[156:157]
	s_add_i32 m0, s73, 0xc000
	ds_read_b128 v[188:191], v174
	ds_read_b128 v[192:195], v174 offset:1024
	ds_read_b128 v[196:199], v174 offset:2048
	ds_read_b128 v[200:203], v174 offset:3072
	ds_read_b128 v[206:209], v174 offset:4096
	ds_read_b128 v[210:213], v174 offset:5120
	ds_read_b128 v[214:217], v174 offset:6144
	ds_read_b128 v[218:221], v174 offset:7168
	global_load_lds_dwordx4 v[168:169], off
	v_lshl_add_u64 v[168:169], s[64:65], 0, v[158:159]
	s_add_i32 m0, s73, 0xe000
	s_nop 0
	global_load_lds_dwordx4 v[168:169], off
	s_waitcnt vmcnt(8)
	s_waitcnt lgkmcnt(0)
	s_barrier
	s_setprio 1
	s_waitcnt lgkmcnt(0)
	v_mfma_f32_16x16x32_bf16 v[126:129], v[130:133], v[188:191], 0
	v_mfma_f32_16x16x32_bf16 v[122:125], v[138:141], v[188:191], 0
	v_mfma_f32_16x16x32_bf16 v[110:113], v[130:133], v[196:199], 0
	v_mfma_f32_16x16x32_bf16 v[106:109], v[138:141], v[196:199], 0
	v_mfma_f32_16x16x32_bf16 v[94:97], v[130:133], v[206:209], 0
	v_mfma_f32_16x16x32_bf16 v[90:93], v[138:141], v[206:209], 0
	v_mfma_f32_16x16x32_bf16 v[78:81], v[130:133], v[214:217], 0
	v_mfma_f32_16x16x32_bf16 v[74:77], v[138:141], v[214:217], 0
	v_mfma_f32_16x16x32_bf16 v[126:129], v[134:137], v[192:195], v[126:129]
	v_mfma_f32_16x16x32_bf16 v[122:125], v[142:145], v[192:195], v[122:125]
	v_mfma_f32_16x16x32_bf16 v[110:113], v[134:137], v[200:203], v[110:113]
	v_mfma_f32_16x16x32_bf16 v[106:109], v[142:145], v[200:203], v[106:109]
	v_mfma_f32_16x16x32_bf16 v[94:97], v[134:137], v[210:213], v[94:97]
	v_mfma_f32_16x16x32_bf16 v[90:93], v[142:145], v[210:213], v[90:93]
	v_mfma_f32_16x16x32_bf16 v[78:81], v[134:137], v[218:221], v[78:81]
	v_mfma_f32_16x16x32_bf16 v[74:77], v[142:145], v[218:221], v[74:77]
	s_setprio 0
	s_setprio 1
	v_mfma_f32_16x16x32_bf16 v[118:121], v[164:167], v[188:191], 0
	v_mfma_f32_16x16x32_bf16 v[114:117], v[180:183], v[188:191], 0
	v_mfma_f32_16x16x32_bf16 v[102:105], v[164:167], v[196:199], 0
	v_mfma_f32_16x16x32_bf16 v[98:101], v[180:183], v[196:199], 0
	v_mfma_f32_16x16x32_bf16 v[86:89], v[164:167], v[206:209], 0
	v_mfma_f32_16x16x32_bf16 v[82:85], v[180:183], v[206:209], 0
	v_mfma_f32_16x16x32_bf16 v[70:73], v[164:167], v[214:217], 0
	v_mfma_f32_16x16x32_bf16 v[66:69], v[180:183], v[214:217], 0
	v_mfma_f32_16x16x32_bf16 v[118:121], v[176:179], v[192:195], v[118:121]
	v_mfma_f32_16x16x32_bf16 v[114:117], v[184:187], v[192:195], v[114:117]
	v_mfma_f32_16x16x32_bf16 v[102:105], v[176:179], v[200:203], v[102:105]
	v_mfma_f32_16x16x32_bf16 v[98:101], v[184:187], v[200:203], v[98:101]
	v_mfma_f32_16x16x32_bf16 v[86:89], v[176:179], v[210:213], v[86:89]
	v_mfma_f32_16x16x32_bf16 v[82:85], v[184:187], v[210:213], v[82:85]
	v_mfma_f32_16x16x32_bf16 v[70:73], v[176:179], v[218:221], v[70:73]
	v_mfma_f32_16x16x32_bf16 v[66:69], v[184:187], v[218:221], v[66:69]
	s_setprio 0
	s_barrier
	s_add_i32 s25, s82, s70
	v_lshl_add_u64 v[168:169], s[66:67], 0, v[150:151]
	s_mov_b32 m0, s25
	ds_read_b128 v[188:191], v174 offset:16384
	ds_read_b128 v[192:195], v174 offset:17408
	ds_read_b128 v[196:199], v174 offset:18432
	ds_read_b128 v[200:203], v174 offset:19456
	ds_read_b128 v[206:209], v174 offset:20480
	ds_read_b128 v[210:213], v174 offset:21504
	ds_read_b128 v[214:217], v174 offset:22528
	ds_read_b128 v[218:221], v174 offset:23552
	global_load_lds_dwordx4 v[168:169], off
	s_add_i32 m0, s25, 0x2000
	s_add_u32 s28, s66, 0x40000
	v_lshl_add_u64 v[222:223], s[66:67], 0, v[146:147]
	s_addc_u32 s29, s67, 0
	s_add_i32 s25, s83, s70
	global_load_lds_dwordx4 v[222:223], off
	v_lshl_add_u64 v[224:225], s[28:29], 0, v[150:151]
	s_mov_b32 m0, s25
	v_lshl_add_u64 v[226:227], s[68:69], 0, v[148:149]
	global_load_lds_dwordx4 v[224:225], off
	v_lshl_add_u64 v[224:225], s[28:29], 0, v[146:147]
	s_add_i32 m0, s25, 0x2000
	s_nop 0
	global_load_lds_dwordx4 v[224:225], off
	v_lshl_add_u64 v[224:225], s[68:69], 0, v[152:153]
	s_mov_b32 m0, s73
	s_nop 0
	global_load_lds_dwordx4 v[224:225], off
	s_mov_b32 m0, s74
	s_nop 0
	global_load_lds_dwordx4 v[226:227], off
	s_waitcnt vmcnt(8)
	s_waitcnt lgkmcnt(0)
	s_barrier
	s_setprio 1
	s_waitcnt lgkmcnt(0)
	v_mfma_f32_16x16x32_bf16 v[62:65], v[130:133], v[188:191], 0
	v_mfma_f32_16x16x32_bf16 v[58:61], v[138:141], v[188:191], 0
	v_mfma_f32_16x16x32_bf16 v[46:49], v[130:133], v[196:199], 0
	v_mfma_f32_16x16x32_bf16 v[42:45], v[138:141], v[196:199], 0
	v_mfma_f32_16x16x32_bf16 v[30:33], v[130:133], v[206:209], 0
	v_mfma_f32_16x16x32_bf16 v[26:29], v[138:141], v[206:209], 0
	v_mfma_f32_16x16x32_bf16 v[14:17], v[130:133], v[214:217], 0
	v_mfma_f32_16x16x32_bf16 v[10:13], v[138:141], v[214:217], 0
	v_mfma_f32_16x16x32_bf16 v[62:65], v[134:137], v[192:195], v[62:65]
	v_mfma_f32_16x16x32_bf16 v[58:61], v[142:145], v[192:195], v[58:61]
	v_mfma_f32_16x16x32_bf16 v[46:49], v[134:137], v[200:203], v[46:49]
	v_mfma_f32_16x16x32_bf16 v[42:45], v[142:145], v[200:203], v[42:45]
	v_mfma_f32_16x16x32_bf16 v[30:33], v[134:137], v[210:213], v[30:33]
	v_mfma_f32_16x16x32_bf16 v[26:29], v[142:145], v[210:213], v[26:29]
	v_mfma_f32_16x16x32_bf16 v[14:17], v[134:137], v[218:221], v[14:17]
	v_mfma_f32_16x16x32_bf16 v[10:13], v[142:145], v[218:221], v[10:13]
	s_setprio 0
	s_setprio 1
	v_mfma_f32_16x16x32_bf16 v[54:57], v[164:167], v[188:191], 0
	v_mfma_f32_16x16x32_bf16 v[50:53], v[180:183], v[188:191], 0
	v_mfma_f32_16x16x32_bf16 v[38:41], v[164:167], v[196:199], 0
	v_mfma_f32_16x16x32_bf16 v[34:37], v[180:183], v[196:199], 0
	v_mfma_f32_16x16x32_bf16 v[22:25], v[164:167], v[206:209], 0
	v_mfma_f32_16x16x32_bf16 v[18:21], v[180:183], v[206:209], 0
	v_mfma_f32_16x16x32_bf16 v[6:9], v[164:167], v[214:217], 0
	v_mfma_f32_16x16x32_bf16 v[2:5], v[180:183], v[214:217], 0
	v_mfma_f32_16x16x32_bf16 v[54:57], v[176:179], v[192:195], v[54:57]
	v_mfma_f32_16x16x32_bf16 v[50:53], v[184:187], v[192:195], v[50:53]
	v_mfma_f32_16x16x32_bf16 v[38:41], v[176:179], v[200:203], v[38:41]
	v_mfma_f32_16x16x32_bf16 v[34:37], v[184:187], v[200:203], v[34:37]
	v_mfma_f32_16x16x32_bf16 v[22:25], v[176:179], v[210:213], v[22:25]
	v_mfma_f32_16x16x32_bf16 v[18:21], v[184:187], v[210:213], v[18:21]
	v_mfma_f32_16x16x32_bf16 v[6:9], v[176:179], v[218:221], v[6:9]
	v_mfma_f32_16x16x32_bf16 v[2:5], v[184:187], v[218:221], v[2:5]
	s_setprio 0
	s_barrier
	s_add_i32 s25, 0, 0x18000
	s_add_i32 s30, 0, 0x1c000
	v_add_u32_e32 v142, s25, v171
	v_add_u32_e32 v175, s30, v171
	ds_read_b128 v[130:133], v142
	ds_read_b128 v[134:137], v142 offset:1024
	ds_read_b128 v[138:141], v142 offset:2048
	ds_read_b128 v[142:145], v142 offset:3072
	ds_read_b128 v[164:167], v175
	ds_read_b128 v[176:179], v175 offset:1024
	ds_read_b128 v[180:183], v175 offset:2048
	ds_read_b128 v[184:187], v175 offset:3072
	s_add_u32 s28, s68, 0x40000
	s_addc_u32 s29, s69, 0
	s_mov_b32 m0, s75
	v_lshl_add_u64 v[228:229], s[28:29], 0, v[152:153]
	ds_read_b128 v[188:191], v174 offset:32768
	ds_read_b128 v[192:195], v174 offset:33792
	ds_read_b128 v[196:199], v174 offset:34816
	ds_read_b128 v[200:203], v174 offset:35840
	ds_read_b128 v[206:209], v174 offset:36864
	ds_read_b128 v[210:213], v174 offset:37888
	ds_read_b128 v[214:217], v174 offset:38912
	ds_read_b128 v[218:221], v174 offset:39936
	global_load_lds_dwordx4 v[228:229], off
	v_lshl_add_u64 v[228:229], s[28:29], 0, v[148:149]
	s_mov_b32 m0, s76
	s_nop 0
	global_load_lds_dwordx4 v[228:229], off
	s_waitcnt vmcnt(8)
	s_waitcnt lgkmcnt(0)
	s_barrier
	s_setprio 1
	s_waitcnt lgkmcnt(0)
	v_mfma_f32_16x16x32_bf16 v[126:129], v[130:133], v[188:191], v[126:129]
	v_mfma_f32_16x16x32_bf16 v[122:125], v[138:141], v[188:191], v[122:125]
	v_mfma_f32_16x16x32_bf16 v[110:113], v[130:133], v[196:199], v[110:113]
	v_mfma_f32_16x16x32_bf16 v[106:109], v[138:141], v[196:199], v[106:109]
	v_mfma_f32_16x16x32_bf16 v[94:97], v[130:133], v[206:209], v[94:97]
	v_mfma_f32_16x16x32_bf16 v[90:93], v[138:141], v[206:209], v[90:93]
	v_mfma_f32_16x16x32_bf16 v[78:81], v[130:133], v[214:217], v[78:81]
	v_mfma_f32_16x16x32_bf16 v[74:77], v[138:141], v[214:217], v[74:77]
	v_mfma_f32_16x16x32_bf16 v[126:129], v[134:137], v[192:195], v[126:129]
	v_mfma_f32_16x16x32_bf16 v[122:125], v[142:145], v[192:195], v[122:125]
	v_mfma_f32_16x16x32_bf16 v[110:113], v[134:137], v[200:203], v[110:113]
	v_mfma_f32_16x16x32_bf16 v[106:109], v[142:145], v[200:203], v[106:109]
	v_mfma_f32_16x16x32_bf16 v[94:97], v[134:137], v[210:213], v[94:97]
	v_mfma_f32_16x16x32_bf16 v[90:93], v[142:145], v[210:213], v[90:93]
	v_mfma_f32_16x16x32_bf16 v[78:81], v[134:137], v[218:221], v[78:81]
	v_mfma_f32_16x16x32_bf16 v[74:77], v[142:145], v[218:221], v[74:77]
	s_setprio 0
	s_setprio 1
	v_mfma_f32_16x16x32_bf16 v[118:121], v[164:167], v[188:191], v[118:121]
	v_mfma_f32_16x16x32_bf16 v[114:117], v[180:183], v[188:191], v[114:117]
	v_mfma_f32_16x16x32_bf16 v[102:105], v[164:167], v[196:199], v[102:105]
	v_mfma_f32_16x16x32_bf16 v[98:101], v[180:183], v[196:199], v[98:101]
	v_mfma_f32_16x16x32_bf16 v[86:89], v[164:167], v[206:209], v[86:89]
	v_mfma_f32_16x16x32_bf16 v[82:85], v[180:183], v[206:209], v[82:85]
	v_mfma_f32_16x16x32_bf16 v[70:73], v[164:167], v[214:217], v[70:73]
	v_mfma_f32_16x16x32_bf16 v[66:69], v[180:183], v[214:217], v[66:69]
	v_mfma_f32_16x16x32_bf16 v[118:121], v[176:179], v[192:195], v[118:121]
	v_mfma_f32_16x16x32_bf16 v[114:117], v[184:187], v[192:195], v[114:117]
	v_mfma_f32_16x16x32_bf16 v[102:105], v[176:179], v[200:203], v[102:105]
	v_mfma_f32_16x16x32_bf16 v[98:101], v[184:187], v[200:203], v[98:101]
	v_mfma_f32_16x16x32_bf16 v[86:89], v[176:179], v[210:213], v[86:89]
	v_mfma_f32_16x16x32_bf16 v[82:85], v[184:187], v[210:213], v[82:85]
	v_mfma_f32_16x16x32_bf16 v[70:73], v[176:179], v[218:221], v[70:73]
	v_mfma_f32_16x16x32_bf16 v[66:69], v[184:187], v[218:221], v[66:69]
	s_setprio 0
	s_barrier
	s_add_i32 s25, s25, s70
	v_lshl_add_u64 v[168:169], v[168:169], 0, s[36:37]
	s_mov_b32 m0, s25
	ds_read_b128 v[188:191], v174 offset:49152
	ds_read_b128 v[192:195], v174 offset:50176
	ds_read_b128 v[196:199], v174 offset:51200
	ds_read_b128 v[200:203], v174 offset:52224
	ds_read_b128 v[206:209], v174 offset:53248
	ds_read_b128 v[210:213], v174 offset:54272
	ds_read_b128 v[214:217], v174 offset:55296
	ds_read_b128 v[218:221], v174 offset:56320
	global_load_lds_dwordx4 v[168:169], off
	s_add_i32 m0, s25, 0x2000
	s_add_u32 s28, s66, 0x40080
	v_lshl_add_u64 v[168:169], v[222:223], 0, s[36:37]
	s_addc_u32 s29, s67, 0
	s_add_i32 s25, s30, s70
	global_load_lds_dwordx4 v[168:169], off
	v_lshl_add_u64 v[168:169], s[28:29], 0, v[150:151]
	s_mov_b32 m0, s25
	s_nop 0
	global_load_lds_dwordx4 v[168:169], off
	v_lshl_add_u64 v[168:169], s[28:29], 0, v[146:147]
	s_add_i32 m0, s25, 0x2000
	s_nop 0
	global_load_lds_dwordx4 v[168:169], off
	v_lshl_add_u64 v[168:169], v[224:225], 0, s[36:37]
	s_mov_b32 m0, s79
	s_nop 0
	global_load_lds_dwordx4 v[168:169], off
	v_lshl_add_u64 v[168:169], v[226:227], 0, s[36:37]
	s_mov_b32 m0, s80
	s_nop 0
	global_load_lds_dwordx4 v[168:169], off
	s_waitcnt vmcnt(8)
	s_waitcnt lgkmcnt(0)
	s_barrier
	s_setprio 1
	s_waitcnt lgkmcnt(0)
	v_mfma_f32_16x16x32_bf16 v[62:65], v[130:133], v[188:191], v[62:65]
	v_mfma_f32_16x16x32_bf16 v[58:61], v[138:141], v[188:191], v[58:61]
	v_mfma_f32_16x16x32_bf16 v[46:49], v[130:133], v[196:199], v[46:49]
	v_mfma_f32_16x16x32_bf16 v[42:45], v[138:141], v[196:199], v[42:45]
	v_mfma_f32_16x16x32_bf16 v[30:33], v[130:133], v[206:209], v[30:33]
	v_mfma_f32_16x16x32_bf16 v[26:29], v[138:141], v[206:209], v[26:29]
	v_mfma_f32_16x16x32_bf16 v[14:17], v[130:133], v[214:217], v[14:17]
	v_mfma_f32_16x16x32_bf16 v[10:13], v[138:141], v[214:217], v[10:13]
	v_mfma_f32_16x16x32_bf16 v[62:65], v[134:137], v[192:195], v[62:65]
	v_mfma_f32_16x16x32_bf16 v[58:61], v[142:145], v[192:195], v[58:61]
	v_mfma_f32_16x16x32_bf16 v[46:49], v[134:137], v[200:203], v[46:49]
	v_mfma_f32_16x16x32_bf16 v[42:45], v[142:145], v[200:203], v[42:45]
	v_mfma_f32_16x16x32_bf16 v[30:33], v[134:137], v[210:213], v[30:33]
	v_mfma_f32_16x16x32_bf16 v[26:29], v[142:145], v[210:213], v[26:29]
	v_mfma_f32_16x16x32_bf16 v[14:17], v[134:137], v[218:221], v[14:17]
	v_mfma_f32_16x16x32_bf16 v[10:13], v[142:145], v[218:221], v[10:13]
	s_setprio 0
	s_setprio 1
	v_mfma_f32_16x16x32_bf16 v[54:57], v[164:167], v[188:191], v[54:57]
	v_mfma_f32_16x16x32_bf16 v[50:53], v[180:183], v[188:191], v[50:53]
	v_mfma_f32_16x16x32_bf16 v[38:41], v[164:167], v[196:199], v[38:41]
	v_mfma_f32_16x16x32_bf16 v[34:37], v[180:183], v[196:199], v[34:37]
	v_mfma_f32_16x16x32_bf16 v[22:25], v[164:167], v[206:209], v[22:25]
	v_mfma_f32_16x16x32_bf16 v[18:21], v[180:183], v[206:209], v[18:21]
	v_mfma_f32_16x16x32_bf16 v[6:9], v[164:167], v[214:217], v[6:9]
	v_mfma_f32_16x16x32_bf16 v[2:5], v[180:183], v[214:217], v[2:5]
	v_mfma_f32_16x16x32_bf16 v[54:57], v[176:179], v[192:195], v[54:57]
	v_mfma_f32_16x16x32_bf16 v[50:53], v[184:187], v[192:195], v[50:53]
	v_mfma_f32_16x16x32_bf16 v[38:41], v[176:179], v[200:203], v[38:41]
	v_mfma_f32_16x16x32_bf16 v[34:37], v[184:187], v[200:203], v[34:37]
	v_mfma_f32_16x16x32_bf16 v[22:25], v[176:179], v[210:213], v[22:25]
	v_mfma_f32_16x16x32_bf16 v[18:21], v[184:187], v[210:213], v[18:21]
	v_mfma_f32_16x16x32_bf16 v[6:9], v[176:179], v[218:221], v[6:9]
	v_mfma_f32_16x16x32_bf16 v[2:5], v[184:187], v[218:221], v[2:5]
	s_setprio 0
	s_barrier
	s_add_i32 s24, s24, 2
	s_add_u32 s64, s64, 0x100
	s_addc_u32 s65, s65, 0
	s_add_u32 s18, s18, 0x100
	s_addc_u32 s19, s19, 0
	s_cmp_gt_u32 s24, 13

.LBB0_1427:
	s_add_u32 s90, s35, s86
	s_addc_u32 s91, s64, s87
	s_and_b64 s[14:15], s[88:89], exec
	s_cselect_b32 s14, s91, s11
	s_cselect_b32 s15, s90, s10
	s_add_u32 s92, s65, s74
	s_addc_u32 s93, s68, s75
	s_and_b64 s[66:67], s[88:89], exec
	s_cselect_b32 s51, s93, s95
	s_cselect_b32 s84, s92, s94
	s_add_i32 s85, s18, -2
	s_add_u32 s10, s10, 0x40080
	s_addc_u32 s11, s11, 0
	s_add_u32 vcc_lo, s94, 0x100
	s_addc_u32 vcc_hi, s95, 0
	s_mov_b32 s94, 0
	s_waitcnt vmcnt(0)
	s_add_i32 s66, s94, 2
	s_add_u32 s67, s10, 0xfffc0080
	s_addc_u32 s72, s11, -1
	s_cmp_eq_u32 s85, s94
	s_cselect_b32 s97, s14, s72
	s_cselect_b32 s96, s15, s67
	s_cselect_b32 s95, s51, vcc_hi
	s_cselect_b32 s94, s84, vcc_lo
	s_add_i32 s67, 0, 0x10000
	s_add_i32 s62, 0, 0x14000
	v_add_u32_e32 v126, s67, v199
	v_add_u32_e32 v158, s62, v199
	ds_read_b128 v[114:117], v126
	ds_read_b128 v[118:121], v126 offset:1024
	ds_read_b128 v[122:125], v126 offset:2048
	ds_read_b128 v[126:129], v126 offset:3072
	ds_read_b128 v[146:149], v158
	ds_read_b128 v[150:153], v158 offset:1024
	ds_read_b128 v[154:157], v158 offset:2048
	ds_read_b128 v[158:161], v158 offset:3072
	v_lshl_add_u64 v[202:203], s[10:11], 0, v[196:197]
	s_add_i32 m0, s28, 0xc000
	ds_read_b128 v[162:165], v214
	ds_read_b128 v[166:169], v214 offset:1024
	ds_read_b128 v[216:219], v214 offset:2048
	ds_read_b128 v[220:223], v214 offset:3072
	ds_read_b128 v[224:227], v214 offset:4096
	ds_read_b128 v[228:231], v214 offset:5120
	ds_read_b128 v[232:235], v214 offset:6144
	ds_read_b128 v[236:239], v214 offset:7168
	global_load_lds_dwordx4 v[202:203], off
	v_lshl_add_u64 v[202:203], s[10:11], 0, v[176:177]
	s_add_i32 m0, s28, 0xe000
	s_nop 0
	global_load_lds_dwordx4 v[202:203], off
	s_waitcnt vmcnt(8)
	s_waitcnt lgkmcnt(0)
	s_barrier
	s_setprio 1
	s_waitcnt lgkmcnt(0)
	v_mfma_f32_16x16x32_bf16 v[142:145], v[114:117], v[162:165], 0
	v_mfma_f32_16x16x32_bf16 v[138:141], v[122:125], v[162:165], 0
	v_mfma_f32_16x16x32_bf16 v[110:113], v[114:117], v[216:219], 0
	v_mfma_f32_16x16x32_bf16 v[106:109], v[122:125], v[216:219], 0
	v_mfma_f32_16x16x32_bf16 v[98:101], v[114:117], v[224:227], 0
	v_mfma_f32_16x16x32_bf16 v[90:93], v[122:125], v[224:227], 0
	v_mfma_f32_16x16x32_bf16 v[82:85], v[114:117], v[232:235], 0
	v_mfma_f32_16x16x32_bf16 v[74:77], v[122:125], v[232:235], 0
	v_mfma_f32_16x16x32_bf16 v[142:145], v[118:121], v[166:169], v[142:145]
	v_mfma_f32_16x16x32_bf16 v[138:141], v[126:129], v[166:169], v[138:141]
	v_mfma_f32_16x16x32_bf16 v[110:113], v[118:121], v[220:223], v[110:113]
	v_mfma_f32_16x16x32_bf16 v[106:109], v[126:129], v[220:223], v[106:109]
	v_mfma_f32_16x16x32_bf16 v[98:101], v[118:121], v[228:231], v[98:101]
	v_mfma_f32_16x16x32_bf16 v[90:93], v[126:129], v[228:231], v[90:93]
	v_mfma_f32_16x16x32_bf16 v[82:85], v[118:121], v[236:239], v[82:85]
	v_mfma_f32_16x16x32_bf16 v[74:77], v[126:129], v[236:239], v[74:77]
	s_setprio 0
	s_setprio 1
	v_mfma_f32_16x16x32_bf16 v[134:137], v[146:149], v[162:165], 0
	v_mfma_f32_16x16x32_bf16 v[130:133], v[154:157], v[162:165], 0
	v_mfma_f32_16x16x32_bf16 v[102:105], v[146:149], v[216:219], 0
	v_mfma_f32_16x16x32_bf16 v[94:97], v[154:157], v[216:219], 0
	v_mfma_f32_16x16x32_bf16 v[86:89], v[146:149], v[224:227], 0
	v_mfma_f32_16x16x32_bf16 v[78:81], v[154:157], v[224:227], 0
	v_mfma_f32_16x16x32_bf16 v[70:73], v[146:149], v[232:235], 0
	v_mfma_f32_16x16x32_bf16 v[66:69], v[154:157], v[232:235], 0
	v_mfma_f32_16x16x32_bf16 v[134:137], v[150:153], v[166:169], v[134:137]
	v_mfma_f32_16x16x32_bf16 v[130:133], v[158:161], v[166:169], v[130:133]
	v_mfma_f32_16x16x32_bf16 v[102:105], v[150:153], v[220:223], v[102:105]
	v_mfma_f32_16x16x32_bf16 v[94:97], v[158:161], v[220:223], v[94:97]
	v_mfma_f32_16x16x32_bf16 v[86:89], v[150:153], v[228:231], v[86:89]
	v_mfma_f32_16x16x32_bf16 v[78:81], v[158:161], v[228:231], v[78:81]
	v_mfma_f32_16x16x32_bf16 v[70:73], v[150:153], v[236:239], v[70:73]
	v_mfma_f32_16x16x32_bf16 v[66:69], v[158:161], v[236:239], v[66:69]
	s_setprio 0
	s_barrier
	s_add_i32 s63, s67, s17
	v_lshl_add_u64 v[202:203], s[94:95], 0, v[174:175]
	s_mov_b32 m0, s63
	ds_read_b128 v[162:165], v214 offset:16384
	ds_read_b128 v[166:169], v214 offset:17408
	ds_read_b128 v[216:219], v214 offset:18432
	ds_read_b128 v[220:223], v214 offset:19456
	ds_read_b128 v[224:227], v214 offset:20480
	ds_read_b128 v[228:231], v214 offset:21504
	ds_read_b128 v[232:235], v214 offset:22528
	ds_read_b128 v[236:239], v214 offset:23552
	global_load_lds_dwordx4 v[202:203], off
	s_add_i32 m0, s63, 0x2000
	s_add_u32 s72, s94, 0x40000
	v_lshl_add_u64 v[240:241], s[94:95], 0, v[178:179]
	s_addc_u32 s73, s95, 0
	s_add_i32 s62, s62, s17
	global_load_lds_dwordx4 v[240:241], off
	v_lshl_add_u64 v[242:243], s[72:73], 0, v[174:175]
	s_mov_b32 m0, s62
	v_lshl_add_u64 v[244:245], s[96:97], 0, v[176:177]
	global_load_lds_dwordx4 v[242:243], off
	v_lshl_add_u64 v[242:243], s[72:73], 0, v[178:179]
	s_add_i32 m0, s62, 0x2000
	s_nop 0
	global_load_lds_dwordx4 v[242:243], off
	v_lshl_add_u64 v[242:243], s[96:97], 0, v[172:173]
	s_mov_b32 m0, s28
	s_nop 0
	global_load_lds_dwordx4 v[242:243], off
	s_mov_b32 m0, s29
	s_nop 0
	global_load_lds_dwordx4 v[244:245], off
	s_waitcnt vmcnt(8)
	s_waitcnt lgkmcnt(0)
	s_barrier
	s_setprio 1
	s_waitcnt lgkmcnt(0)
	v_mfma_f32_16x16x32_bf16 v[62:65], v[114:117], v[162:165], 0
	v_mfma_f32_16x16x32_bf16 v[58:61], v[122:125], v[162:165], 0
	v_mfma_f32_16x16x32_bf16 v[50:53], v[114:117], v[216:219], 0
	v_mfma_f32_16x16x32_bf16 v[42:45], v[122:125], v[216:219], 0
	v_mfma_f32_16x16x32_bf16 v[34:37], v[114:117], v[224:227], 0
	v_mfma_f32_16x16x32_bf16 v[26:29], v[122:125], v[224:227], 0
	v_mfma_f32_16x16x32_bf16 v[18:21], v[114:117], v[232:235], 0
	v_mfma_f32_16x16x32_bf16 v[10:13], v[122:125], v[232:235], 0
	v_mfma_f32_16x16x32_bf16 v[62:65], v[118:121], v[166:169], v[62:65]
	v_mfma_f32_16x16x32_bf16 v[58:61], v[126:129], v[166:169], v[58:61]
	v_mfma_f32_16x16x32_bf16 v[50:53], v[118:121], v[220:223], v[50:53]
	v_mfma_f32_16x16x32_bf16 v[42:45], v[126:129], v[220:223], v[42:45]
	v_mfma_f32_16x16x32_bf16 v[34:37], v[118:121], v[228:231], v[34:37]
	v_mfma_f32_16x16x32_bf16 v[26:29], v[126:129], v[228:231], v[26:29]
	v_mfma_f32_16x16x32_bf16 v[18:21], v[118:121], v[236:239], v[18:21]
	v_mfma_f32_16x16x32_bf16 v[10:13], v[126:129], v[236:239], v[10:13]
	s_setprio 0
	s_setprio 1
	v_mfma_f32_16x16x32_bf16 v[54:57], v[146:149], v[162:165], 0
	v_mfma_f32_16x16x32_bf16 v[46:49], v[154:157], v[162:165], 0
	v_mfma_f32_16x16x32_bf16 v[38:41], v[146:149], v[216:219], 0
	v_mfma_f32_16x16x32_bf16 v[30:33], v[154:157], v[216:219], 0
	v_mfma_f32_16x16x32_bf16 v[22:25], v[146:149], v[224:227], 0
	v_mfma_f32_16x16x32_bf16 v[14:17], v[154:157], v[224:227], 0
	v_mfma_f32_16x16x32_bf16 v[6:9], v[146:149], v[232:235], 0
	v_mfma_f32_16x16x32_bf16 v[2:5], v[154:157], v[232:235], 0
	v_mfma_f32_16x16x32_bf16 v[54:57], v[150:153], v[166:169], v[54:57]
	v_mfma_f32_16x16x32_bf16 v[46:49], v[158:161], v[166:169], v[46:49]
	v_mfma_f32_16x16x32_bf16 v[38:41], v[150:153], v[220:223], v[38:41]
	v_mfma_f32_16x16x32_bf16 v[30:33], v[158:161], v[220:223], v[30:33]
	v_mfma_f32_16x16x32_bf16 v[22:25], v[150:153], v[228:231], v[22:25]
	v_mfma_f32_16x16x32_bf16 v[14:17], v[158:161], v[228:231], v[14:17]
	v_mfma_f32_16x16x32_bf16 v[6:9], v[150:153], v[236:239], v[6:9]
	v_mfma_f32_16x16x32_bf16 v[2:5], v[158:161], v[236:239], v[2:5]
	s_setprio 0
	s_barrier
	s_add_i32 s62, 0, 0x18000
	s_add_i32 s63, 0, 0x1c000
	v_add_u32_e32 v126, s62, v199
	v_add_u32_e32 v158, s63, v199
	ds_read_b128 v[114:117], v126
	ds_read_b128 v[118:121], v126 offset:1024
	ds_read_b128 v[122:125], v126 offset:2048
	ds_read_b128 v[126:129], v126 offset:3072
	ds_read_b128 v[146:149], v158
	ds_read_b128 v[150:153], v158 offset:1024
	ds_read_b128 v[154:157], v158 offset:2048
	ds_read_b128 v[158:161], v158 offset:3072
	s_add_u32 s72, s96, 0x40000
	s_addc_u32 s73, s97, 0
	s_mov_b32 m0, s30
	v_lshl_add_u64 v[246:247], s[72:73], 0, v[172:173]
	ds_read_b128 v[162:165], v214 offset:32768
	ds_read_b128 v[166:169], v214 offset:33792
	ds_read_b128 v[216:219], v214 offset:34816
	ds_read_b128 v[220:223], v214 offset:35840
	ds_read_b128 v[224:227], v214 offset:36864
	ds_read_b128 v[228:231], v214 offset:37888
	ds_read_b128 v[232:235], v214 offset:38912
	ds_read_b128 v[236:239], v214 offset:39936
	global_load_lds_dwordx4 v[246:247], off
	v_lshl_add_u64 v[246:247], s[72:73], 0, v[176:177]
	s_mov_b32 m0, s31
	s_nop 0
	global_load_lds_dwordx4 v[246:247], off
	s_waitcnt vmcnt(8)
	s_waitcnt lgkmcnt(0)
	s_barrier
	s_setprio 1
	s_waitcnt lgkmcnt(0)
	v_mfma_f32_16x16x32_bf16 v[142:145], v[114:117], v[162:165], v[142:145]
	v_mfma_f32_16x16x32_bf16 v[138:141], v[122:125], v[162:165], v[138:141]
	v_mfma_f32_16x16x32_bf16 v[110:113], v[114:117], v[216:219], v[110:113]
	v_mfma_f32_16x16x32_bf16 v[106:109], v[122:125], v[216:219], v[106:109]
	v_mfma_f32_16x16x32_bf16 v[98:101], v[114:117], v[224:227], v[98:101]
	v_mfma_f32_16x16x32_bf16 v[90:93], v[122:125], v[224:227], v[90:93]
	v_mfma_f32_16x16x32_bf16 v[82:85], v[114:117], v[232:235], v[82:85]
	v_mfma_f32_16x16x32_bf16 v[74:77], v[122:125], v[232:235], v[74:77]
	v_mfma_f32_16x16x32_bf16 v[142:145], v[118:121], v[166:169], v[142:145]
	v_mfma_f32_16x16x32_bf16 v[138:141], v[126:129], v[166:169], v[138:141]
	v_mfma_f32_16x16x32_bf16 v[110:113], v[118:121], v[220:223], v[110:113]
	v_mfma_f32_16x16x32_bf16 v[106:109], v[126:129], v[220:223], v[106:109]
	v_mfma_f32_16x16x32_bf16 v[98:101], v[118:121], v[228:231], v[98:101]
	v_mfma_f32_16x16x32_bf16 v[90:93], v[126:129], v[228:231], v[90:93]
	v_mfma_f32_16x16x32_bf16 v[82:85], v[118:121], v[236:239], v[82:85]
	v_mfma_f32_16x16x32_bf16 v[74:77], v[126:129], v[236:239], v[74:77]
	s_setprio 0
	s_setprio 1
	v_mfma_f32_16x16x32_bf16 v[134:137], v[146:149], v[162:165], v[134:137]
	v_mfma_f32_16x16x32_bf16 v[130:133], v[154:157], v[162:165], v[130:133]
	v_mfma_f32_16x16x32_bf16 v[102:105], v[146:149], v[216:219], v[102:105]
	v_mfma_f32_16x16x32_bf16 v[94:97], v[154:157], v[216:219], v[94:97]
	v_mfma_f32_16x16x32_bf16 v[86:89], v[146:149], v[224:227], v[86:89]
	v_mfma_f32_16x16x32_bf16 v[78:81], v[154:157], v[224:227], v[78:81]
	v_mfma_f32_16x16x32_bf16 v[70:73], v[146:149], v[232:235], v[70:73]
	v_mfma_f32_16x16x32_bf16 v[66:69], v[154:157], v[232:235], v[66:69]
	v_mfma_f32_16x16x32_bf16 v[134:137], v[150:153], v[166:169], v[134:137]
	v_mfma_f32_16x16x32_bf16 v[130:133], v[158:161], v[166:169], v[130:133]
	v_mfma_f32_16x16x32_bf16 v[102:105], v[150:153], v[220:223], v[102:105]
	v_mfma_f32_16x16x32_bf16 v[94:97], v[158:161], v[220:223], v[94:97]
	v_mfma_f32_16x16x32_bf16 v[86:89], v[150:153], v[228:231], v[86:89]
	v_mfma_f32_16x16x32_bf16 v[78:81], v[158:161], v[228:231], v[78:81]
	v_mfma_f32_16x16x32_bf16 v[70:73], v[150:153], v[236:239], v[70:73]
	v_mfma_f32_16x16x32_bf16 v[66:69], v[158:161], v[236:239], v[66:69]
	s_setprio 0
	s_barrier
	s_add_i32 s62, s62, s17
	v_lshl_add_u64 v[202:203], v[202:203], 0, s[76:77]
	s_mov_b32 m0, s62
	ds_read_b128 v[162:165], v214 offset:49152
	ds_read_b128 v[166:169], v214 offset:50176
	ds_read_b128 v[216:219], v214 offset:51200
	ds_read_b128 v[220:223], v214 offset:52224
	ds_read_b128 v[224:227], v214 offset:53248
	ds_read_b128 v[228:231], v214 offset:54272
	ds_read_b128 v[232:235], v214 offset:55296
	ds_read_b128 v[236:239], v214 offset:56320
	global_load_lds_dwordx4 v[202:203], off
	s_add_i32 m0, s62, 0x2000
	s_add_u32 s72, s94, 0x40080
	v_lshl_add_u64 v[202:203], v[240:241], 0, s[76:77]
	s_addc_u32 s73, s95, 0
	s_add_i32 s62, s63, s17
	global_load_lds_dwordx4 v[202:203], off
	v_lshl_add_u64 v[202:203], s[72:73], 0, v[174:175]
	s_mov_b32 m0, s62
	s_nop 0
	global_load_lds_dwordx4 v[202:203], off
	v_lshl_add_u64 v[202:203], s[72:73], 0, v[178:179]
	s_add_i32 m0, s62, 0x2000
	s_nop 0
	global_load_lds_dwordx4 v[202:203], off
	v_lshl_add_u64 v[202:203], v[242:243], 0, s[76:77]
	s_mov_b32 m0, s44
	s_nop 0
	global_load_lds_dwordx4 v[202:203], off
	v_lshl_add_u64 v[202:203], v[244:245], 0, s[76:77]
	s_mov_b32 m0, s36
	s_nop 0
	global_load_lds_dwordx4 v[202:203], off
	s_waitcnt vmcnt(8)
	s_waitcnt lgkmcnt(0)
	s_barrier
	s_setprio 1
	s_waitcnt lgkmcnt(0)
	v_mfma_f32_16x16x32_bf16 v[62:65], v[114:117], v[162:165], v[62:65]
	v_mfma_f32_16x16x32_bf16 v[58:61], v[122:125], v[162:165], v[58:61]
	v_mfma_f32_16x16x32_bf16 v[50:53], v[114:117], v[216:219], v[50:53]
	v_mfma_f32_16x16x32_bf16 v[42:45], v[122:125], v[216:219], v[42:45]
	v_mfma_f32_16x16x32_bf16 v[34:37], v[114:117], v[224:227], v[34:37]
	v_mfma_f32_16x16x32_bf16 v[26:29], v[122:125], v[224:227], v[26:29]
	v_mfma_f32_16x16x32_bf16 v[18:21], v[114:117], v[232:235], v[18:21]
	v_mfma_f32_16x16x32_bf16 v[10:13], v[122:125], v[232:235], v[10:13]
	v_mfma_f32_16x16x32_bf16 v[62:65], v[118:121], v[166:169], v[62:65]
	v_mfma_f32_16x16x32_bf16 v[58:61], v[126:129], v[166:169], v[58:61]
	v_mfma_f32_16x16x32_bf16 v[50:53], v[118:121], v[220:223], v[50:53]
	v_mfma_f32_16x16x32_bf16 v[42:45], v[126:129], v[220:223], v[42:45]
	v_mfma_f32_16x16x32_bf16 v[34:37], v[118:121], v[228:231], v[34:37]
	v_mfma_f32_16x16x32_bf16 v[26:29], v[126:129], v[228:231], v[26:29]
	v_mfma_f32_16x16x32_bf16 v[18:21], v[118:121], v[236:239], v[18:21]
	v_mfma_f32_16x16x32_bf16 v[10:13], v[126:129], v[236:239], v[10:13]
	s_setprio 0
	s_setprio 1
	v_mfma_f32_16x16x32_bf16 v[54:57], v[146:149], v[162:165], v[54:57]
	v_mfma_f32_16x16x32_bf16 v[46:49], v[154:157], v[162:165], v[46:49]
	v_mfma_f32_16x16x32_bf16 v[38:41], v[146:149], v[216:219], v[38:41]
	v_mfma_f32_16x16x32_bf16 v[30:33], v[154:157], v[216:219], v[30:33]
	v_mfma_f32_16x16x32_bf16 v[22:25], v[146:149], v[224:227], v[22:25]
	v_mfma_f32_16x16x32_bf16 v[14:17], v[154:157], v[224:227], v[14:17]
	v_mfma_f32_16x16x32_bf16 v[6:9], v[146:149], v[232:235], v[6:9]
	v_mfma_f32_16x16x32_bf16 v[2:5], v[154:157], v[232:235], v[2:5]
	v_mfma_f32_16x16x32_bf16 v[54:57], v[150:153], v[166:169], v[54:57]
	v_mfma_f32_16x16x32_bf16 v[46:49], v[158:161], v[166:169], v[46:49]
	v_mfma_f32_16x16x32_bf16 v[38:41], v[150:153], v[220:223], v[38:41]
	v_mfma_f32_16x16x32_bf16 v[30:33], v[158:161], v[220:223], v[30:33]
	v_mfma_f32_16x16x32_bf16 v[22:25], v[150:153], v[228:231], v[22:25]
	v_mfma_f32_16x16x32_bf16 v[14:17], v[158:161], v[228:231], v[14:17]
	v_mfma_f32_16x16x32_bf16 v[6:9], v[150:153], v[236:239], v[6:9]
	v_mfma_f32_16x16x32_bf16 v[2:5], v[158:161], v[236:239], v[2:5]
	s_setprio 0
	s_barrier
	s_add_u32 s10, s10, 0x100
	s_addc_u32 s11, s11, 0
	s_add_u32 vcc_lo, vcc_lo, 0x100
	s_addc_u32 vcc_hi, vcc_hi, 0
	s_cmp_ge_i32 s66, s18
	s_mov_b32 s94, s66

.LBB0_1618:
	s_add_u32 s24, s96, s20
	s_addc_u32 s25, s97, s21
	s_and_b64 s[14:15], s[4:5], exec
	s_cselect_b32 s14, s25, s29
	s_cselect_b32 s15, s24, s28
	s_add_u32 s26, s2, s22
	s_addc_u32 s27, s3, s23
	s_and_b64 s[36:37], s[4:5], exec
	s_cselect_b32 s17, s27, s31
	s_cselect_b32 s49, s26, s30
	s_add_u32 s28, s28, 0x40080
	s_addc_u32 s29, s29, 0
	s_add_u32 s50, s30, 0x100
	s_addc_u32 s51, s31, 0
	s_mov_b32 s62, -2
	ds_read_b128 v[154:157], v150
	ds_read_b128 v[158:161], v150 offset:1024
	ds_read_b128 v[162:165], v150 offset:2048
	ds_read_b128 v[166:169], v150 offset:3072
	ds_read_b128 v[170:173], v151
	ds_read_b128 v[174:177], v151 offset:1024
	ds_read_b128 v[178:181], v151 offset:2048
	ds_read_b128 v[182:185], v151 offset:3072
	s_add_u32 s30, s28, 0xfffc0080
	s_addc_u32 s31, s29, -1
	s_cmp_eq_u32 s62, 12
	s_cselect_b32 s37, s14, s31
	s_cselect_b32 s36, s15, s30
	s_cselect_b32 s31, s17, s51
	s_cselect_b32 s30, s49, s50
	v_lshl_add_u64 v[146:147], s[28:29], 0, v[138:139]
	s_add_i32 m0, s19, 0xc000
	ds_read_b128 v[186:189], v152
	ds_read_b128 v[190:193], v152 offset:1024
	ds_read_b128 v[194:197], v152 offset:2048
	ds_read_b128 v[198:201], v152 offset:3072
	ds_read_b128 v[206:209], v152 offset:4096
	ds_read_b128 v[210:213], v152 offset:5120
	ds_read_b128 v[214:217], v152 offset:6144
	ds_read_b128 v[218:221], v152 offset:7168
	global_load_lds_dwordx4 v[146:147], off
	v_lshl_add_u64 v[146:147], s[28:29], 0, v[140:141]
	s_add_i32 m0, s19, 0xe000
	s_nop 0
	global_load_lds_dwordx4 v[146:147], off
	s_waitcnt vmcnt(8)
	s_waitcnt lgkmcnt(0)
	s_barrier
	s_setprio 1
	s_waitcnt lgkmcnt(0)
	v_mfma_f32_16x16x32_bf16 v[126:129], v[154:157], v[186:189], 0
	v_mfma_f32_16x16x32_bf16 v[122:125], v[162:165], v[186:189], 0
	v_mfma_f32_16x16x32_bf16 v[110:113], v[154:157], v[194:197], 0
	v_mfma_f32_16x16x32_bf16 v[106:109], v[162:165], v[194:197], 0
	v_mfma_f32_16x16x32_bf16 v[94:97], v[154:157], v[206:209], 0
	v_mfma_f32_16x16x32_bf16 v[90:93], v[162:165], v[206:209], 0
	v_mfma_f32_16x16x32_bf16 v[78:81], v[154:157], v[214:217], 0
	v_mfma_f32_16x16x32_bf16 v[74:77], v[162:165], v[214:217], 0
	v_mfma_f32_16x16x32_bf16 v[126:129], v[158:161], v[190:193], v[126:129]
	v_mfma_f32_16x16x32_bf16 v[122:125], v[166:169], v[190:193], v[122:125]
	v_mfma_f32_16x16x32_bf16 v[110:113], v[158:161], v[198:201], v[110:113]
	v_mfma_f32_16x16x32_bf16 v[106:109], v[166:169], v[198:201], v[106:109]
	v_mfma_f32_16x16x32_bf16 v[94:97], v[158:161], v[210:213], v[94:97]
	v_mfma_f32_16x16x32_bf16 v[90:93], v[166:169], v[210:213], v[90:93]
	v_mfma_f32_16x16x32_bf16 v[78:81], v[158:161], v[218:221], v[78:81]
	v_mfma_f32_16x16x32_bf16 v[74:77], v[166:169], v[218:221], v[74:77]
	s_setprio 0
	s_setprio 1
	v_mfma_f32_16x16x32_bf16 v[118:121], v[170:173], v[186:189], 0
	v_mfma_f32_16x16x32_bf16 v[114:117], v[178:181], v[186:189], 0
	v_mfma_f32_16x16x32_bf16 v[102:105], v[170:173], v[194:197], 0
	v_mfma_f32_16x16x32_bf16 v[98:101], v[178:181], v[194:197], 0
	v_mfma_f32_16x16x32_bf16 v[86:89], v[170:173], v[206:209], 0
	v_mfma_f32_16x16x32_bf16 v[82:85], v[178:181], v[206:209], 0
	v_mfma_f32_16x16x32_bf16 v[70:73], v[170:173], v[214:217], 0
	v_mfma_f32_16x16x32_bf16 v[66:69], v[178:181], v[214:217], 0
	v_mfma_f32_16x16x32_bf16 v[118:121], v[174:177], v[190:193], v[118:121]
	v_mfma_f32_16x16x32_bf16 v[114:117], v[182:185], v[190:193], v[114:117]
	v_mfma_f32_16x16x32_bf16 v[102:105], v[174:177], v[198:201], v[102:105]
	v_mfma_f32_16x16x32_bf16 v[98:101], v[182:185], v[198:201], v[98:101]
	v_mfma_f32_16x16x32_bf16 v[86:89], v[174:177], v[210:213], v[86:89]
	v_mfma_f32_16x16x32_bf16 v[82:85], v[182:185], v[210:213], v[82:85]
	v_mfma_f32_16x16x32_bf16 v[70:73], v[174:177], v[218:221], v[70:73]
	v_mfma_f32_16x16x32_bf16 v[66:69], v[182:185], v[218:221], v[66:69]
	s_setprio 0
	s_barrier
	s_add_i32 s63, s45, s12
	v_lshl_add_u64 v[146:147], s[30:31], 0, v[134:135]
	s_mov_b32 m0, s63
	ds_read_b128 v[186:189], v152 offset:16384
	ds_read_b128 v[190:193], v152 offset:17408
	ds_read_b128 v[194:197], v152 offset:18432
	ds_read_b128 v[198:201], v152 offset:19456
	ds_read_b128 v[206:209], v152 offset:20480
	ds_read_b128 v[210:213], v152 offset:21504
	ds_read_b128 v[214:217], v152 offset:22528
	ds_read_b128 v[218:221], v152 offset:23552
	global_load_lds_dwordx4 v[146:147], off
	s_add_i32 m0, s63, 0x2000
	s_add_u32 s64, s30, 0x40000
	v_lshl_add_u64 v[202:203], s[30:31], 0, v[130:131]
	s_addc_u32 s65, s31, 0
	s_add_i32 s63, s46, s12
	global_load_lds_dwordx4 v[202:203], off
	v_lshl_add_u64 v[222:223], s[64:65], 0, v[134:135]
	s_mov_b32 m0, s63
	v_lshl_add_u64 v[224:225], s[36:37], 0, v[132:133]
	global_load_lds_dwordx4 v[222:223], off
	v_lshl_add_u64 v[222:223], s[64:65], 0, v[130:131]
	s_add_i32 m0, s63, 0x2000
	s_nop 0
	global_load_lds_dwordx4 v[222:223], off
	v_lshl_add_u64 v[222:223], s[36:37], 0, v[136:137]
	s_mov_b32 m0, s19
	s_nop 0
	global_load_lds_dwordx4 v[222:223], off
	s_mov_b32 m0, s33
	s_nop 0
	global_load_lds_dwordx4 v[224:225], off
	s_waitcnt vmcnt(8)
	s_waitcnt lgkmcnt(0)
	s_barrier
	s_setprio 1
	s_waitcnt lgkmcnt(0)
	v_mfma_f32_16x16x32_bf16 v[62:65], v[154:157], v[186:189], 0
	v_mfma_f32_16x16x32_bf16 v[58:61], v[162:165], v[186:189], 0
	v_mfma_f32_16x16x32_bf16 v[46:49], v[154:157], v[194:197], 0
	v_mfma_f32_16x16x32_bf16 v[42:45], v[162:165], v[194:197], 0
	v_mfma_f32_16x16x32_bf16 v[30:33], v[154:157], v[206:209], 0
	v_mfma_f32_16x16x32_bf16 v[26:29], v[162:165], v[206:209], 0
	v_mfma_f32_16x16x32_bf16 v[14:17], v[154:157], v[214:217], 0
	v_mfma_f32_16x16x32_bf16 v[10:13], v[162:165], v[214:217], 0
	v_mfma_f32_16x16x32_bf16 v[62:65], v[158:161], v[190:193], v[62:65]
	v_mfma_f32_16x16x32_bf16 v[58:61], v[166:169], v[190:193], v[58:61]
	v_mfma_f32_16x16x32_bf16 v[46:49], v[158:161], v[198:201], v[46:49]
	v_mfma_f32_16x16x32_bf16 v[42:45], v[166:169], v[198:201], v[42:45]
	v_mfma_f32_16x16x32_bf16 v[30:33], v[158:161], v[210:213], v[30:33]
	v_mfma_f32_16x16x32_bf16 v[26:29], v[166:169], v[210:213], v[26:29]
	v_mfma_f32_16x16x32_bf16 v[14:17], v[158:161], v[218:221], v[14:17]
	v_mfma_f32_16x16x32_bf16 v[10:13], v[166:169], v[218:221], v[10:13]
	s_setprio 0
	s_setprio 1
	v_mfma_f32_16x16x32_bf16 v[54:57], v[170:173], v[186:189], 0
	v_mfma_f32_16x16x32_bf16 v[50:53], v[178:181], v[186:189], 0
	v_mfma_f32_16x16x32_bf16 v[38:41], v[170:173], v[194:197], 0
	v_mfma_f32_16x16x32_bf16 v[34:37], v[178:181], v[194:197], 0
	v_mfma_f32_16x16x32_bf16 v[22:25], v[170:173], v[206:209], 0
	v_mfma_f32_16x16x32_bf16 v[18:21], v[178:181], v[206:209], 0
	v_mfma_f32_16x16x32_bf16 v[6:9], v[170:173], v[214:217], 0
	v_mfma_f32_16x16x32_bf16 v[2:5], v[178:181], v[214:217], 0
	v_mfma_f32_16x16x32_bf16 v[54:57], v[174:177], v[190:193], v[54:57]
	v_mfma_f32_16x16x32_bf16 v[50:53], v[182:185], v[190:193], v[50:53]
	v_mfma_f32_16x16x32_bf16 v[38:41], v[174:177], v[198:201], v[38:41]
	v_mfma_f32_16x16x32_bf16 v[34:37], v[182:185], v[198:201], v[34:37]
	v_mfma_f32_16x16x32_bf16 v[22:25], v[174:177], v[210:213], v[22:25]
	v_mfma_f32_16x16x32_bf16 v[18:21], v[182:185], v[210:213], v[18:21]
	v_mfma_f32_16x16x32_bf16 v[6:9], v[174:177], v[218:221], v[6:9]
	v_mfma_f32_16x16x32_bf16 v[2:5], v[182:185], v[218:221], v[2:5]
	s_setprio 0
	s_barrier
	s_add_i32 s63, 0, 0x18000
	v_add_u32_e32 v153, s63, v149
	s_add_i32 s64, 0, 0x1c000
	ds_read_b128 v[154:157], v153
	ds_read_b128 v[158:161], v153 offset:1024
	ds_read_b128 v[162:165], v153 offset:2048
	ds_read_b128 v[166:169], v153 offset:3072
	v_add_u32_e32 v153, s64, v149
	ds_read_b128 v[170:173], v153
	ds_read_b128 v[174:177], v153 offset:1024
	ds_read_b128 v[178:181], v153 offset:2048
	ds_read_b128 v[182:185], v153 offset:3072
	s_add_u32 s36, s36, 0x40000
	s_addc_u32 s37, s37, 0
	s_mov_b32 m0, s35
	v_lshl_add_u64 v[226:227], s[36:37], 0, v[136:137]
	ds_read_b128 v[186:189], v152 offset:32768
	ds_read_b128 v[190:193], v152 offset:33792
	ds_read_b128 v[194:197], v152 offset:34816
	ds_read_b128 v[198:201], v152 offset:35840
	ds_read_b128 v[206:209], v152 offset:36864
	ds_read_b128 v[210:213], v152 offset:37888
	ds_read_b128 v[214:217], v152 offset:38912
	ds_read_b128 v[218:221], v152 offset:39936
	global_load_lds_dwordx4 v[226:227], off
	v_lshl_add_u64 v[226:227], s[36:37], 0, v[132:133]
	s_mov_b32 m0, s38
	s_nop 0
	global_load_lds_dwordx4 v[226:227], off
	s_waitcnt vmcnt(8)
	s_waitcnt lgkmcnt(0)
	s_barrier
	s_setprio 1
	s_waitcnt lgkmcnt(0)
	v_mfma_f32_16x16x32_bf16 v[126:129], v[154:157], v[186:189], v[126:129]
	v_mfma_f32_16x16x32_bf16 v[122:125], v[162:165], v[186:189], v[122:125]
	v_mfma_f32_16x16x32_bf16 v[110:113], v[154:157], v[194:197], v[110:113]
	v_mfma_f32_16x16x32_bf16 v[106:109], v[162:165], v[194:197], v[106:109]
	v_mfma_f32_16x16x32_bf16 v[94:97], v[154:157], v[206:209], v[94:97]
	v_mfma_f32_16x16x32_bf16 v[90:93], v[162:165], v[206:209], v[90:93]
	v_mfma_f32_16x16x32_bf16 v[78:81], v[154:157], v[214:217], v[78:81]
	v_mfma_f32_16x16x32_bf16 v[74:77], v[162:165], v[214:217], v[74:77]
	v_mfma_f32_16x16x32_bf16 v[126:129], v[158:161], v[190:193], v[126:129]
	v_mfma_f32_16x16x32_bf16 v[122:125], v[166:169], v[190:193], v[122:125]
	v_mfma_f32_16x16x32_bf16 v[110:113], v[158:161], v[198:201], v[110:113]
	v_mfma_f32_16x16x32_bf16 v[106:109], v[166:169], v[198:201], v[106:109]
	v_mfma_f32_16x16x32_bf16 v[94:97], v[158:161], v[210:213], v[94:97]
	v_mfma_f32_16x16x32_bf16 v[90:93], v[166:169], v[210:213], v[90:93]
	v_mfma_f32_16x16x32_bf16 v[78:81], v[158:161], v[218:221], v[78:81]
	v_mfma_f32_16x16x32_bf16 v[74:77], v[166:169], v[218:221], v[74:77]
	s_setprio 0
	s_setprio 1
	v_mfma_f32_16x16x32_bf16 v[118:121], v[170:173], v[186:189], v[118:121]
	v_mfma_f32_16x16x32_bf16 v[114:117], v[178:181], v[186:189], v[114:117]
	v_mfma_f32_16x16x32_bf16 v[102:105], v[170:173], v[194:197], v[102:105]
	v_mfma_f32_16x16x32_bf16 v[98:101], v[178:181], v[194:197], v[98:101]
	v_mfma_f32_16x16x32_bf16 v[86:89], v[170:173], v[206:209], v[86:89]
	v_mfma_f32_16x16x32_bf16 v[82:85], v[178:181], v[206:209], v[82:85]
	v_mfma_f32_16x16x32_bf16 v[70:73], v[170:173], v[214:217], v[70:73]
	v_mfma_f32_16x16x32_bf16 v[66:69], v[178:181], v[214:217], v[66:69]
	v_mfma_f32_16x16x32_bf16 v[118:121], v[174:177], v[190:193], v[118:121]
	v_mfma_f32_16x16x32_bf16 v[114:117], v[182:185], v[190:193], v[114:117]
	v_mfma_f32_16x16x32_bf16 v[102:105], v[174:177], v[198:201], v[102:105]
	v_mfma_f32_16x16x32_bf16 v[98:101], v[182:185], v[198:201], v[98:101]
	v_mfma_f32_16x16x32_bf16 v[86:89], v[174:177], v[210:213], v[86:89]
	v_mfma_f32_16x16x32_bf16 v[82:85], v[182:185], v[210:213], v[82:85]
	v_mfma_f32_16x16x32_bf16 v[70:73], v[174:177], v[218:221], v[70:73]
	v_mfma_f32_16x16x32_bf16 v[66:69], v[182:185], v[218:221], v[66:69]
	s_setprio 0
	s_barrier
	s_add_i32 s36, s63, s12
	v_lshl_add_u64 v[146:147], v[146:147], 0, s[8:9]
	s_mov_b32 m0, s36
	ds_read_b128 v[186:189], v152 offset:49152
	ds_read_b128 v[190:193], v152 offset:50176
	ds_read_b128 v[194:197], v152 offset:51200
	ds_read_b128 v[198:201], v152 offset:52224
	ds_read_b128 v[206:209], v152 offset:53248
	ds_read_b128 v[210:213], v152 offset:54272
	ds_read_b128 v[214:217], v152 offset:55296
	ds_read_b128 v[218:221], v152 offset:56320
	global_load_lds_dwordx4 v[146:147], off
	s_add_i32 m0, s36, 0x2000
	s_add_u32 s30, s30, 0x40080
	v_lshl_add_u64 v[146:147], v[202:203], 0, s[8:9]
	s_addc_u32 s31, s31, 0
	s_add_i32 s36, s64, s12
	global_load_lds_dwordx4 v[146:147], off
	v_lshl_add_u64 v[146:147], s[30:31], 0, v[134:135]
	s_mov_b32 m0, s36
	s_nop 0
	global_load_lds_dwordx4 v[146:147], off
	v_lshl_add_u64 v[146:147], s[30:31], 0, v[130:131]
	s_add_i32 m0, s36, 0x2000
	s_nop 0
	global_load_lds_dwordx4 v[146:147], off
	v_lshl_add_u64 v[146:147], v[222:223], 0, s[8:9]
	s_mov_b32 m0, s42
	s_nop 0
	global_load_lds_dwordx4 v[146:147], off
	v_lshl_add_u64 v[146:147], v[224:225], 0, s[8:9]
	s_mov_b32 m0, s43
	s_nop 0
	global_load_lds_dwordx4 v[146:147], off
	s_waitcnt vmcnt(8)
	s_waitcnt lgkmcnt(0)
	s_barrier
	s_setprio 1
	s_waitcnt lgkmcnt(0)
	v_mfma_f32_16x16x32_bf16 v[62:65], v[154:157], v[186:189], v[62:65]
	v_mfma_f32_16x16x32_bf16 v[58:61], v[162:165], v[186:189], v[58:61]
	v_mfma_f32_16x16x32_bf16 v[46:49], v[154:157], v[194:197], v[46:49]
	v_mfma_f32_16x16x32_bf16 v[42:45], v[162:165], v[194:197], v[42:45]
	v_mfma_f32_16x16x32_bf16 v[30:33], v[154:157], v[206:209], v[30:33]
	v_mfma_f32_16x16x32_bf16 v[26:29], v[162:165], v[206:209], v[26:29]
	v_mfma_f32_16x16x32_bf16 v[14:17], v[154:157], v[214:217], v[14:17]
	v_mfma_f32_16x16x32_bf16 v[10:13], v[162:165], v[214:217], v[10:13]
	v_mfma_f32_16x16x32_bf16 v[62:65], v[158:161], v[190:193], v[62:65]
	v_mfma_f32_16x16x32_bf16 v[58:61], v[166:169], v[190:193], v[58:61]
	v_mfma_f32_16x16x32_bf16 v[46:49], v[158:161], v[198:201], v[46:49]
	v_mfma_f32_16x16x32_bf16 v[42:45], v[166:169], v[198:201], v[42:45]
	v_mfma_f32_16x16x32_bf16 v[30:33], v[158:161], v[210:213], v[30:33]
	v_mfma_f32_16x16x32_bf16 v[26:29], v[166:169], v[210:213], v[26:29]
	v_mfma_f32_16x16x32_bf16 v[14:17], v[158:161], v[218:221], v[14:17]
	v_mfma_f32_16x16x32_bf16 v[10:13], v[166:169], v[218:221], v[10:13]
	s_setprio 0
	s_setprio 1
	v_mfma_f32_16x16x32_bf16 v[54:57], v[170:173], v[186:189], v[54:57]
	v_mfma_f32_16x16x32_bf16 v[50:53], v[178:181], v[186:189], v[50:53]
	v_mfma_f32_16x16x32_bf16 v[38:41], v[170:173], v[194:197], v[38:41]
	v_mfma_f32_16x16x32_bf16 v[34:37], v[178:181], v[194:197], v[34:37]
	v_mfma_f32_16x16x32_bf16 v[22:25], v[170:173], v[206:209], v[22:25]
	v_mfma_f32_16x16x32_bf16 v[18:21], v[178:181], v[206:209], v[18:21]
	v_mfma_f32_16x16x32_bf16 v[6:9], v[170:173], v[214:217], v[6:9]
	v_mfma_f32_16x16x32_bf16 v[2:5], v[178:181], v[214:217], v[2:5]
	v_mfma_f32_16x16x32_bf16 v[54:57], v[174:177], v[190:193], v[54:57]
	v_mfma_f32_16x16x32_bf16 v[50:53], v[182:185], v[190:193], v[50:53]
	v_mfma_f32_16x16x32_bf16 v[38:41], v[174:177], v[198:201], v[38:41]
	v_mfma_f32_16x16x32_bf16 v[34:37], v[182:185], v[198:201], v[34:37]
	v_mfma_f32_16x16x32_bf16 v[22:25], v[174:177], v[210:213], v[22:25]
	v_mfma_f32_16x16x32_bf16 v[18:21], v[182:185], v[210:213], v[18:21]
	v_mfma_f32_16x16x32_bf16 v[6:9], v[174:177], v[218:221], v[6:9]
	v_mfma_f32_16x16x32_bf16 v[2:5], v[182:185], v[218:221], v[2:5]
	s_setprio 0
	s_barrier
	s_add_i32 s62, s62, 2
	s_add_u32 s28, s28, 0x100
	s_addc_u32 s29, s29, 0
	s_add_u32 s50, s50, 0x100
	s_addc_u32 s51, s51, 0
	s_cmp_gt_u32 s62, 13

.LBB0_1707:
	v_readlane_b32 s46, v249, 32
	v_readlane_b32 s47, v249, 33
	s_add_u32 s46, s46, s42
	s_addc_u32 s47, s47, s43
	s_and_b64 s[48:49], s[44:45], exec
	s_cselect_b32 s34, s47, s51
	s_cselect_b32 s66, s46, s50
	s_add_u32 s48, s35, s40
	s_addc_u32 s49, s70, s41
	s_and_b64 s[64:65], s[44:45], exec
	s_cselect_b32 s67, s49, s63
	s_cselect_b32 s68, s48, s62
	s_add_i32 s69, s7, -2
	s_add_u32 s50, s50, 0x100080
	s_addc_u32 s51, s51, 0
	s_add_u32 s91, s62, 0x100
	s_addc_u32 s92, s63, 0
	s_mov_b32 s62, 0
	s_waitcnt vmcnt(0)
	ds_read_b128 v[130:133], v168
	ds_read_b128 v[134:137], v168 offset:1024
	ds_read_b128 v[138:141], v168 offset:2048
	ds_read_b128 v[142:145], v168 offset:3072
	ds_read_b128 v[162:165], v169
	ds_read_b128 v[172:175], v169 offset:1024
	ds_read_b128 v[176:179], v169 offset:2048
	ds_read_b128 v[180:183], v169 offset:3072
	s_add_i32 s93, s62, 2
	s_add_u32 s63, s50, 0xfff00080
	s_addc_u32 s64, s51, -1
	s_cmp_eq_u32 s69, s62
	s_cselect_b32 s62, s68, s91
	s_cselect_b32 s65, s34, s64
	s_cselect_b32 s64, s66, s63
	s_cselect_b32 s63, s67, s92
	v_lshl_add_u64 v[218:219], s[50:51], 0, v[156:157]
	s_add_i32 m0, s12, 0xc000
	ds_read_b128 v[184:187], v170
	ds_read_b128 v[188:191], v170 offset:1024
	ds_read_b128 v[192:195], v170 offset:2048
	ds_read_b128 v[196:199], v170 offset:3072
	ds_read_b128 v[200:203], v170 offset:4096
	ds_read_b128 v[206:209], v170 offset:5120
	ds_read_b128 v[210:213], v170 offset:6144
	ds_read_b128 v[214:217], v170 offset:7168
	global_load_lds_dwordx4 v[218:219], off
	v_lshl_add_u64 v[218:219], s[50:51], 0, v[158:159]
	s_add_i32 m0, s12, 0xe000
	s_nop 0
	global_load_lds_dwordx4 v[218:219], off
	s_waitcnt vmcnt(8)
	s_waitcnt lgkmcnt(0)
	s_barrier
	s_setprio 1
	s_waitcnt lgkmcnt(0)
	v_mfma_f32_16x16x32_bf16 v[126:129], v[130:133], v[184:187], 0
	v_mfma_f32_16x16x32_bf16 v[122:125], v[138:141], v[184:187], 0
	v_mfma_f32_16x16x32_bf16 v[110:113], v[130:133], v[192:195], 0
	v_mfma_f32_16x16x32_bf16 v[106:109], v[138:141], v[192:195], 0
	v_mfma_f32_16x16x32_bf16 v[98:101], v[130:133], v[200:203], 0
	v_mfma_f32_16x16x32_bf16 v[90:93], v[138:141], v[200:203], 0
	v_mfma_f32_16x16x32_bf16 v[82:85], v[130:133], v[210:213], 0
	v_mfma_f32_16x16x32_bf16 v[74:77], v[138:141], v[210:213], 0
	v_mfma_f32_16x16x32_bf16 v[126:129], v[134:137], v[188:191], v[126:129]
	v_mfma_f32_16x16x32_bf16 v[122:125], v[142:145], v[188:191], v[122:125]
	v_mfma_f32_16x16x32_bf16 v[110:113], v[134:137], v[196:199], v[110:113]
	v_mfma_f32_16x16x32_bf16 v[106:109], v[142:145], v[196:199], v[106:109]
	v_mfma_f32_16x16x32_bf16 v[98:101], v[134:137], v[206:209], v[98:101]
	v_mfma_f32_16x16x32_bf16 v[90:93], v[142:145], v[206:209], v[90:93]
	v_mfma_f32_16x16x32_bf16 v[82:85], v[134:137], v[214:217], v[82:85]
	v_mfma_f32_16x16x32_bf16 v[74:77], v[142:145], v[214:217], v[74:77]
	s_setprio 0
	s_setprio 1
	v_mfma_f32_16x16x32_bf16 v[118:121], v[162:165], v[184:187], 0
	v_mfma_f32_16x16x32_bf16 v[114:117], v[176:179], v[184:187], 0
	v_mfma_f32_16x16x32_bf16 v[102:105], v[162:165], v[192:195], 0
	v_mfma_f32_16x16x32_bf16 v[94:97], v[176:179], v[192:195], 0
	v_mfma_f32_16x16x32_bf16 v[86:89], v[162:165], v[200:203], 0
	v_mfma_f32_16x16x32_bf16 v[78:81], v[176:179], v[200:203], 0
	v_mfma_f32_16x16x32_bf16 v[70:73], v[162:165], v[210:213], 0
	v_mfma_f32_16x16x32_bf16 v[66:69], v[176:179], v[210:213], 0
	v_mfma_f32_16x16x32_bf16 v[118:121], v[172:175], v[188:191], v[118:121]
	v_mfma_f32_16x16x32_bf16 v[114:117], v[180:183], v[188:191], v[114:117]
	v_mfma_f32_16x16x32_bf16 v[102:105], v[172:175], v[196:199], v[102:105]
	v_mfma_f32_16x16x32_bf16 v[94:97], v[180:183], v[196:199], v[94:97]
	v_mfma_f32_16x16x32_bf16 v[86:89], v[172:175], v[206:209], v[86:89]
	v_mfma_f32_16x16x32_bf16 v[78:81], v[180:183], v[206:209], v[78:81]
	v_mfma_f32_16x16x32_bf16 v[70:73], v[172:175], v[214:217], v[70:73]
	v_mfma_f32_16x16x32_bf16 v[66:69], v[180:183], v[214:217], v[66:69]
	s_setprio 0
	s_barrier
	s_add_i32 s94, s31, s2
	v_lshl_add_u64 v[218:219], s[62:63], 0, v[148:149]
	s_mov_b32 m0, s94
	ds_read_b128 v[184:187], v170 offset:16384
	ds_read_b128 v[188:191], v170 offset:17408
	ds_read_b128 v[192:195], v170 offset:18432
	ds_read_b128 v[196:199], v170 offset:19456
	ds_read_b128 v[200:203], v170 offset:20480
	ds_read_b128 v[206:209], v170 offset:21504
	ds_read_b128 v[210:213], v170 offset:22528
	ds_read_b128 v[214:217], v170 offset:23552
	global_load_lds_dwordx4 v[218:219], off
	s_add_i32 m0, s94, 0x2000
	s_add_u32 s94, s62, 0x100000
	v_lshl_add_u64 v[220:221], s[62:63], 0, v[152:153]
	s_addc_u32 s95, s63, 0
	s_add_i32 s96, s82, s2
	global_load_lds_dwordx4 v[220:221], off
	v_lshl_add_u64 v[222:223], s[94:95], 0, v[148:149]
	s_mov_b32 m0, s96
	v_lshl_add_u64 v[224:225], s[64:65], 0, v[150:151]
	global_load_lds_dwordx4 v[222:223], off
	v_lshl_add_u64 v[222:223], s[94:95], 0, v[152:153]
	s_add_i32 m0, s96, 0x2000
	s_nop 0
	global_load_lds_dwordx4 v[222:223], off
	v_lshl_add_u64 v[222:223], s[64:65], 0, v[146:147]
	s_mov_b32 m0, s12
	s_nop 0
	global_load_lds_dwordx4 v[222:223], off
	s_mov_b32 m0, s13
	s_nop 0
	global_load_lds_dwordx4 v[224:225], off
	s_waitcnt vmcnt(8)
	s_waitcnt lgkmcnt(0)
	s_barrier
	s_setprio 1
	s_waitcnt lgkmcnt(0)
	v_mfma_f32_16x16x32_bf16 v[62:65], v[130:133], v[184:187], 0
	v_mfma_f32_16x16x32_bf16 v[58:61], v[138:141], v[184:187], 0
	v_mfma_f32_16x16x32_bf16 v[50:53], v[130:133], v[192:195], 0
	v_mfma_f32_16x16x32_bf16 v[42:45], v[138:141], v[192:195], 0
	v_mfma_f32_16x16x32_bf16 v[34:37], v[130:133], v[200:203], 0
	v_mfma_f32_16x16x32_bf16 v[26:29], v[138:141], v[200:203], 0
	v_mfma_f32_16x16x32_bf16 v[18:21], v[130:133], v[210:213], 0
	v_mfma_f32_16x16x32_bf16 v[10:13], v[138:141], v[210:213], 0
	v_mfma_f32_16x16x32_bf16 v[62:65], v[134:137], v[188:191], v[62:65]
	v_mfma_f32_16x16x32_bf16 v[58:61], v[142:145], v[188:191], v[58:61]
	v_mfma_f32_16x16x32_bf16 v[50:53], v[134:137], v[196:199], v[50:53]
	v_mfma_f32_16x16x32_bf16 v[42:45], v[142:145], v[196:199], v[42:45]
	v_mfma_f32_16x16x32_bf16 v[34:37], v[134:137], v[206:209], v[34:37]
	v_mfma_f32_16x16x32_bf16 v[26:29], v[142:145], v[206:209], v[26:29]
	v_mfma_f32_16x16x32_bf16 v[18:21], v[134:137], v[214:217], v[18:21]
	v_mfma_f32_16x16x32_bf16 v[10:13], v[142:145], v[214:217], v[10:13]
	s_setprio 0
	s_setprio 1
	v_mfma_f32_16x16x32_bf16 v[54:57], v[162:165], v[184:187], 0
	v_mfma_f32_16x16x32_bf16 v[46:49], v[176:179], v[184:187], 0
	v_mfma_f32_16x16x32_bf16 v[38:41], v[162:165], v[192:195], 0
	v_mfma_f32_16x16x32_bf16 v[30:33], v[176:179], v[192:195], 0
	v_mfma_f32_16x16x32_bf16 v[22:25], v[162:165], v[200:203], 0
	v_mfma_f32_16x16x32_bf16 v[14:17], v[176:179], v[200:203], 0
	v_mfma_f32_16x16x32_bf16 v[6:9], v[162:165], v[210:213], 0
	v_mfma_f32_16x16x32_bf16 v[2:5], v[176:179], v[210:213], 0
	v_mfma_f32_16x16x32_bf16 v[54:57], v[172:175], v[188:191], v[54:57]
	v_mfma_f32_16x16x32_bf16 v[46:49], v[180:183], v[188:191], v[46:49]
	v_mfma_f32_16x16x32_bf16 v[38:41], v[172:175], v[196:199], v[38:41]
	v_mfma_f32_16x16x32_bf16 v[30:33], v[180:183], v[196:199], v[30:33]
	v_mfma_f32_16x16x32_bf16 v[22:25], v[172:175], v[206:209], v[22:25]
	v_mfma_f32_16x16x32_bf16 v[14:17], v[180:183], v[206:209], v[14:17]
	v_mfma_f32_16x16x32_bf16 v[6:9], v[172:175], v[214:217], v[6:9]
	v_mfma_f32_16x16x32_bf16 v[2:5], v[180:183], v[214:217], v[2:5]
	s_setprio 0
	s_barrier
	s_add_i32 s94, 0, 0x18000
	s_add_i32 s95, 0, 0x1c000
	v_add_u32_e32 v142, s94, v167
	v_add_u32_e32 v154, s95, v167
	ds_read_b128 v[130:133], v142
	ds_read_b128 v[134:137], v142 offset:1024
	ds_read_b128 v[138:141], v142 offset:2048
	ds_read_b128 v[142:145], v142 offset:3072
	ds_read_b128 v[162:165], v154
	ds_read_b128 v[172:175], v154 offset:1024
	ds_read_b128 v[176:179], v154 offset:2048
	ds_read_b128 v[180:183], v154 offset:3072
	s_add_u32 s64, s64, 0x100000
	s_addc_u32 s65, s65, 0
	s_mov_b32 m0, s18
	v_lshl_add_u64 v[226:227], s[64:65], 0, v[146:147]
	ds_read_b128 v[184:187], v170 offset:32768
	ds_read_b128 v[188:191], v170 offset:33792
	ds_read_b128 v[192:195], v170 offset:34816
	ds_read_b128 v[196:199], v170 offset:35840
	ds_read_b128 v[200:203], v170 offset:36864
	ds_read_b128 v[206:209], v170 offset:37888
	ds_read_b128 v[210:213], v170 offset:38912
	ds_read_b128 v[214:217], v170 offset:39936
	global_load_lds_dwordx4 v[226:227], off
	v_lshl_add_u64 v[226:227], s[64:65], 0, v[150:151]
	s_mov_b32 m0, s19
	s_nop 0
	global_load_lds_dwordx4 v[226:227], off
	s_waitcnt vmcnt(8)
	s_waitcnt lgkmcnt(0)
	s_barrier
	s_setprio 1
	s_waitcnt lgkmcnt(0)
	v_mfma_f32_16x16x32_bf16 v[126:129], v[130:133], v[184:187], v[126:129]
	v_mfma_f32_16x16x32_bf16 v[122:125], v[138:141], v[184:187], v[122:125]
	v_mfma_f32_16x16x32_bf16 v[110:113], v[130:133], v[192:195], v[110:113]
	v_mfma_f32_16x16x32_bf16 v[106:109], v[138:141], v[192:195], v[106:109]
	v_mfma_f32_16x16x32_bf16 v[98:101], v[130:133], v[200:203], v[98:101]
	v_mfma_f32_16x16x32_bf16 v[90:93], v[138:141], v[200:203], v[90:93]
	v_mfma_f32_16x16x32_bf16 v[82:85], v[130:133], v[210:213], v[82:85]
	v_mfma_f32_16x16x32_bf16 v[74:77], v[138:141], v[210:213], v[74:77]
	v_mfma_f32_16x16x32_bf16 v[126:129], v[134:137], v[188:191], v[126:129]
	v_mfma_f32_16x16x32_bf16 v[122:125], v[142:145], v[188:191], v[122:125]
	v_mfma_f32_16x16x32_bf16 v[110:113], v[134:137], v[196:199], v[110:113]
	v_mfma_f32_16x16x32_bf16 v[106:109], v[142:145], v[196:199], v[106:109]
	v_mfma_f32_16x16x32_bf16 v[98:101], v[134:137], v[206:209], v[98:101]
	v_mfma_f32_16x16x32_bf16 v[90:93], v[142:145], v[206:209], v[90:93]
	v_mfma_f32_16x16x32_bf16 v[82:85], v[134:137], v[214:217], v[82:85]
	v_mfma_f32_16x16x32_bf16 v[74:77], v[142:145], v[214:217], v[74:77]
	s_setprio 0
	s_setprio 1
	v_mfma_f32_16x16x32_bf16 v[118:121], v[162:165], v[184:187], v[118:121]
	v_mfma_f32_16x16x32_bf16 v[114:117], v[176:179], v[184:187], v[114:117]
	v_mfma_f32_16x16x32_bf16 v[102:105], v[162:165], v[192:195], v[102:105]
	v_mfma_f32_16x16x32_bf16 v[94:97], v[176:179], v[192:195], v[94:97]
	v_mfma_f32_16x16x32_bf16 v[86:89], v[162:165], v[200:203], v[86:89]
	v_mfma_f32_16x16x32_bf16 v[78:81], v[176:179], v[200:203], v[78:81]
	v_mfma_f32_16x16x32_bf16 v[70:73], v[162:165], v[210:213], v[70:73]
	v_mfma_f32_16x16x32_bf16 v[66:69], v[176:179], v[210:213], v[66:69]
	v_mfma_f32_16x16x32_bf16 v[118:121], v[172:175], v[188:191], v[118:121]
	v_mfma_f32_16x16x32_bf16 v[114:117], v[180:183], v[188:191], v[114:117]
	v_mfma_f32_16x16x32_bf16 v[102:105], v[172:175], v[196:199], v[102:105]
	v_mfma_f32_16x16x32_bf16 v[94:97], v[180:183], v[196:199], v[94:97]
	v_mfma_f32_16x16x32_bf16 v[86:89], v[172:175], v[206:209], v[86:89]
	v_mfma_f32_16x16x32_bf16 v[78:81], v[180:183], v[206:209], v[78:81]
	v_mfma_f32_16x16x32_bf16 v[70:73], v[172:175], v[214:217], v[70:73]
	v_mfma_f32_16x16x32_bf16 v[66:69], v[180:183], v[214:217], v[66:69]
	s_setprio 0
	s_barrier
	s_add_i32 s64, s94, s2
	v_lshl_add_u64 v[218:219], v[218:219], 0, s[16:17]
	s_mov_b32 m0, s64
	ds_read_b128 v[184:187], v170 offset:49152
	ds_read_b128 v[188:191], v170 offset:50176
	ds_read_b128 v[192:195], v170 offset:51200
	ds_read_b128 v[196:199], v170 offset:52224
	ds_read_b128 v[200:203], v170 offset:53248
	ds_read_b128 v[206:209], v170 offset:54272
	ds_read_b128 v[210:213], v170 offset:55296
	ds_read_b128 v[214:217], v170 offset:56320
	global_load_lds_dwordx4 v[218:219], off
	s_add_i32 m0, s64, 0x2000
	s_add_u32 s62, s62, 0x100080
	v_lshl_add_u64 v[218:219], v[220:221], 0, s[16:17]
	s_addc_u32 s63, s63, 0
	s_add_i32 s64, s95, s2
	global_load_lds_dwordx4 v[218:219], off
	v_lshl_add_u64 v[218:219], s[62:63], 0, v[148:149]
	s_mov_b32 m0, s64
	s_nop 0
	global_load_lds_dwordx4 v[218:219], off
	v_lshl_add_u64 v[218:219], s[62:63], 0, v[152:153]
	s_add_i32 m0, s64, 0x2000
	s_nop 0
	global_load_lds_dwordx4 v[218:219], off
	v_lshl_add_u64 v[218:219], v[222:223], 0, s[16:17]
	s_mov_b32 m0, s74
	s_nop 0
	global_load_lds_dwordx4 v[218:219], off
	v_lshl_add_u64 v[218:219], v[224:225], 0, s[16:17]
	s_mov_b32 m0, s75
	s_nop 0
	global_load_lds_dwordx4 v[218:219], off
	s_waitcnt vmcnt(8)
	s_waitcnt lgkmcnt(0)
	s_barrier
	s_setprio 1
	s_waitcnt lgkmcnt(0)
	v_mfma_f32_16x16x32_bf16 v[62:65], v[130:133], v[184:187], v[62:65]
	v_mfma_f32_16x16x32_bf16 v[58:61], v[138:141], v[184:187], v[58:61]
	v_mfma_f32_16x16x32_bf16 v[50:53], v[130:133], v[192:195], v[50:53]
	v_mfma_f32_16x16x32_bf16 v[42:45], v[138:141], v[192:195], v[42:45]
	v_mfma_f32_16x16x32_bf16 v[34:37], v[130:133], v[200:203], v[34:37]
	v_mfma_f32_16x16x32_bf16 v[26:29], v[138:141], v[200:203], v[26:29]
	v_mfma_f32_16x16x32_bf16 v[18:21], v[130:133], v[210:213], v[18:21]
	v_mfma_f32_16x16x32_bf16 v[10:13], v[138:141], v[210:213], v[10:13]
	v_mfma_f32_16x16x32_bf16 v[62:65], v[134:137], v[188:191], v[62:65]
	v_mfma_f32_16x16x32_bf16 v[58:61], v[142:145], v[188:191], v[58:61]
	v_mfma_f32_16x16x32_bf16 v[50:53], v[134:137], v[196:199], v[50:53]
	v_mfma_f32_16x16x32_bf16 v[42:45], v[142:145], v[196:199], v[42:45]
	v_mfma_f32_16x16x32_bf16 v[34:37], v[134:137], v[206:209], v[34:37]
	v_mfma_f32_16x16x32_bf16 v[26:29], v[142:145], v[206:209], v[26:29]
	v_mfma_f32_16x16x32_bf16 v[18:21], v[134:137], v[214:217], v[18:21]
	v_mfma_f32_16x16x32_bf16 v[10:13], v[142:145], v[214:217], v[10:13]
	s_setprio 0
	s_setprio 1
	v_mfma_f32_16x16x32_bf16 v[54:57], v[162:165], v[184:187], v[54:57]
	v_mfma_f32_16x16x32_bf16 v[46:49], v[176:179], v[184:187], v[46:49]
	v_mfma_f32_16x16x32_bf16 v[38:41], v[162:165], v[192:195], v[38:41]
	v_mfma_f32_16x16x32_bf16 v[30:33], v[176:179], v[192:195], v[30:33]
	v_mfma_f32_16x16x32_bf16 v[22:25], v[162:165], v[200:203], v[22:25]
	v_mfma_f32_16x16x32_bf16 v[14:17], v[176:179], v[200:203], v[14:17]
	v_mfma_f32_16x16x32_bf16 v[6:9], v[162:165], v[210:213], v[6:9]
	v_mfma_f32_16x16x32_bf16 v[2:5], v[176:179], v[210:213], v[2:5]
	v_mfma_f32_16x16x32_bf16 v[54:57], v[172:175], v[188:191], v[54:57]
	v_mfma_f32_16x16x32_bf16 v[46:49], v[180:183], v[188:191], v[46:49]
	v_mfma_f32_16x16x32_bf16 v[38:41], v[172:175], v[196:199], v[38:41]
	v_mfma_f32_16x16x32_bf16 v[30:33], v[180:183], v[196:199], v[30:33]
	v_mfma_f32_16x16x32_bf16 v[22:25], v[172:175], v[206:209], v[22:25]
	v_mfma_f32_16x16x32_bf16 v[14:17], v[180:183], v[206:209], v[14:17]
	v_mfma_f32_16x16x32_bf16 v[6:9], v[172:175], v[214:217], v[6:9]
	v_mfma_f32_16x16x32_bf16 v[2:5], v[180:183], v[214:217], v[2:5]
	s_setprio 0
	s_barrier
	s_add_u32 s50, s50, 0x100
	s_addc_u32 s51, s51, 0
	s_add_u32 s91, s91, 0x100
	s_addc_u32 s92, s92, 0
	s_cmp_ge_i32 s93, s7
	s_mov_b32 s62, s93
